# MLA attention loop: keep O accumulators in fixed registers, removed per-tile 32 v_mov_b64 copies + s_nop 9
# speedup vs baseline: 1.0135x; 1.0135x over previous
; DI unsigned pack2(float a, float b) { bf2_t v = __builtin_convertvector((f32x2){a, b}, bf2_t); return __builtin_bit_cast(unsigned, v); }
; template <int DQK, int MODE, bool QN, bool KN> ...
;     ...
;   float inv = 1.f;
;   if (MODE != 2) { const float lt = l_run + __shfl_xor(l_run, 32); inv = 1.f / lt; }
; #pragma unroll
;   for (int dvb = 0; dvb < 2; ++dvb)
; #pragma unroll
;     for (int g = 0; g < 4; ++g) {
;       u32x2 w;
;       w.x = pack2(o[dvb][4 * g] * inv, o[dvb][4 * g + 1] * inv); w.y = pack2(o[dvb][4 * g + 2] * inv, o[dvb][4 * g + 3] * inv);
;       *(u32x2*)(O + (size_t)(wave * 32 + r) * DM + dvb * 32 + 8 * g + 4 * h) = w;
;     }
;   __syncthreads();
.LBB0_1166:
	v_mov_b64_e32 v[32:33], v[128:129]
	v_mov_b64_e32 v[34:35], v[130:131]
	v_mov_b64_e32 v[36:37], v[132:133]
	v_mov_b64_e32 v[38:39], v[134:135]
	v_mov_b64_e32 v[40:41], v[136:137]
	v_mov_b64_e32 v[42:43], v[138:139]
	v_mov_b64_e32 v[44:45], v[140:141]
	v_mov_b64_e32 v[46:47], v[142:143]
	v_mov_b64_e32 v[48:49], v[96:97]
	v_mov_b64_e32 v[50:51], v[98:99]
	v_mov_b64_e32 v[52:53], v[100:101]
	v_mov_b64_e32 v[54:55], v[102:103]
	v_mov_b64_e32 v[56:57], v[104:105]
	v_mov_b64_e32 v[58:59], v[106:107]
	v_mov_b64_e32 v[60:61], v[108:109]
	v_mov_b64_e32 v[62:63], v[110:111]
	ds_bpermute_b32 v0, v235, v253
	s_lshl_b64 s[0:1], s[6:7], 11
	v_readlane_b32 s2, v254, 23
	s_add_u32 s2, s2, s0
	v_readlane_b32 s0, v254, 24
	s_waitcnt lgkmcnt(0)
	v_add_f32_e32 v0, v253, v0
	s_addc_u32 s3, s0, s1
	v_div_scale_f32 v2, s[0:1], v0, v0, 1.0
	v_rcp_f32_e32 v3, v2
	s_lshl_b32 s0, s44, 1
	s_add_u32 s0, s2, s0
	s_addc_u32 s1, s3, 0
	v_fma_f32 v4, -v2, v3, 1.0
	v_fmac_f32_e32 v3, v4, v3
	v_div_scale_f32 v4, vcc, 1.0, v0, 1.0
	v_mul_f32_e32 v5, v4, v3
	v_fma_f32 v6, -v2, v5, v4
	v_fmac_f32_e32 v5, v6, v3
	v_fma_f32 v2, -v2, v5, v4
	v_div_fmas_f32 v2, v2, v3, v5
	v_div_fixup_f32 v2, v2, v0, 1.0
	v_lshlrev_b64 v[4:5], 11, v[216:217]
	v_lshl_add_u64 v[4:5], s[0:1], 0, v[4:5]
	v_lshlrev_b32_e32 v0, 1, v247
	v_pk_mul_f32 v[6:7], v[48:49], v[2:3] op_sel_hi:[1,0]
	v_pk_mul_f32 v[8:9], v[50:51], v[2:3] op_sel_hi:[1,0]
	v_lshl_add_u64 v[4:5], v[4:5], 0, v[0:1]
	v_cvt_pk_bf16_f32 v6, v6, v7
	v_cvt_pk_bf16_f32 v7, v8, v9
	global_store_dwordx2 v[4:5], v[6:7], off
	v_pk_mul_f32 v[6:7], v[52:53], v[2:3] op_sel_hi:[1,0]
	v_pk_mul_f32 v[8:9], v[54:55], v[2:3] op_sel_hi:[1,0]
	v_cvt_pk_bf16_f32 v6, v6, v7
	v_cvt_pk_bf16_f32 v7, v8, v9
	global_store_dwordx2 v[4:5], v[6:7], off offset:16
	v_pk_mul_f32 v[6:7], v[56:57], v[2:3] op_sel_hi:[1,0]
	v_pk_mul_f32 v[8:9], v[58:59], v[2:3] op_sel_hi:[1,0]
	v_cvt_pk_bf16_f32 v6, v6, v7
	v_cvt_pk_bf16_f32 v7, v8, v9
	global_store_dwordx2 v[4:5], v[6:7], off offset:32
	v_pk_mul_f32 v[6:7], v[60:61], v[2:3] op_sel_hi:[1,0]
	v_pk_mul_f32 v[8:9], v[62:63], v[2:3] op_sel_hi:[1,0]
	v_cvt_pk_bf16_f32 v6, v6, v7
	v_cvt_pk_bf16_f32 v7, v8, v9
	global_store_dwordx2 v[4:5], v[6:7], off offset:48
	v_pk_mul_f32 v[6:7], v[32:33], v[2:3] op_sel_hi:[1,0]
	v_pk_mul_f32 v[8:9], v[34:35], v[2:3] op_sel_hi:[1,0]
	v_cvt_pk_bf16_f32 v6, v6, v7
	v_cvt_pk_bf16_f32 v7, v8, v9
	global_store_dwordx2 v[4:5], v[6:7], off offset:64
	v_pk_mul_f32 v[6:7], v[36:37], v[2:3] op_sel_hi:[1,0]
	v_pk_mul_f32 v[8:9], v[38:39], v[2:3] op_sel_hi:[1,0]
	v_cvt_pk_bf16_f32 v6, v6, v7
	v_cvt_pk_bf16_f32 v7, v8, v9
	global_store_dwordx2 v[4:5], v[6:7], off offset:80
	v_pk_mul_f32 v[6:7], v[40:41], v[2:3] op_sel_hi:[1,0]
	v_pk_mul_f32 v[8:9], v[42:43], v[2:3] op_sel_hi:[1,0]
	v_cvt_pk_bf16_f32 v6, v6, v7
	v_cvt_pk_bf16_f32 v7, v8, v9
	global_store_dwordx2 v[4:5], v[6:7], off offset:96
	v_pk_mul_f32 v[6:7], v[44:45], v[2:3] op_sel_hi:[1,0]
	v_pk_mul_f32 v[2:3], v[46:47], v[2:3] op_sel_hi:[1,0]
	v_cvt_pk_bf16_f32 v6, v6, v7
	v_cvt_pk_bf16_f32 v7, v2, v3
	global_store_dwordx2 v[4:5], v[6:7], off offset:112
	s_barrier

; DI float bf2f(bf16_t v) { return __uint_as_float(((unsigned)v) << 16); }
; template <int DQK, int MODE, bool QN, bool KN> ...
;     ...
; #pragma unroll
;   for (int s = 0; s < NS; ++s) qf[s] = *(const bf16x8*)(Q + (size_t)(wave * 32 + r) * ldq + 16 * s + 8 * h);
;   if (QN) {
;     float qv[NS][8];
;     float ss = 0.f;
; #pragma unroll
;     for (int s = 0; s < NS; ++s)
; #pragma unroll
;       for (int j = 0; j < 8; ++j) { qv[s][j] = bf2f((bf16_t)qf[s][j]); ss += qv[s][j] * qv[s][j]; }
;     ss += __shfl_xor(ss, 32);
;     const float rstd = rsqrtf(ss * (1.f / DQK) + EPS) * oscale;
; #pragma unroll
;     for (int s = 0; s < NS; ++s) {
;       const f32x4 g0 = *(const f32x4*)(gq + 16 * s + 8 * h), g1 = *(const f32x4*)(gq + 16 * s + 8 * h + 4);
; #pragma unroll
;       for (int j = 0; j < 4; ++j) { qv[s][j] *= rstd * g0[j]; qv[s][4 + j] *= rstd * g1[j]; }
;     }
;     if (DQK == 96) {
;       const float pf_ = (float)qpos[wave * 32 + r];
; #pragma unroll
;       for (int j = 0; j < 8; ++j) {
;         const float ang = pf_ * exp2f(-(float)(8 * h + j) * (13.287712379549449f / 16.f));
;         float rev = ang * 0.15915494309189535f; rev = rev - floorf(rev);
;         const float sn = __builtin_amdgcn_sinf(rev), cs = __builtin_amdgcn_cosf(rev);
; template <int LAYER>
; DI void attn_phase(const Params& p, char* smem) {
;     ...
;       const int hl = j >> 4, qi = j & 15, qt = ((j / L) & 1) ? (15 - qi) : qi, bh = hl * 8 + xcd, b = bh / 12, hd = bh % 12, q0 = qt * 256;
;       const size_t tok0 = (size_t)b * SEQ;
;       bf16_t* O = mix + (tok0 + q0) * DM + hd * 64;
;       if (LAYER == 0) {
;         const bf16_t* P = (const bf16_t*)(ws + O_P);
;         attn_item<64, 2, false, false>(P + (tok0 + q0) * 2560 + hd * 64, 2560, P + tok0 * 2560 + 768 + hd * 64, 2560, P + tok0 * 2560 + 1536 + hd * 64, 2560,
;                                        q0, q0 / 64 + 4, O, 0.125f, smem, nullptr, 1.f, nullptr, nullptr);
;       } else {
;         const bf16_t* Qb = (const bf16_t*)(ws + O_QB);
;         const bf16_t* Kn = (const bf16_t*)(ws + O_KN);
;         const bf16_t* V1 = (const bf16_t*)(ws + O_V1);
;         attn_item<96, 1, true, false>(Qb + (tok0 + q0) * 1152 + hd * 96, 1152, Kn + tok0 * 1152 + hd * 96, 1152, V1 + tok0 * 768 + hd * 64, 768,
;                                       q0, q0 / 64 + 4, O, 1.f, smem, p.mla_g_qn, 0.14724138410008716f, p.pos + tok0 + q0, p.mla_g_kn);
.LBB0_1194:
	s_and_b64 vcc, exec, s[0:1]
	s_cbranch_vccz .LBB0_1167
	v_readlane_b32 s0, v254, 22
	s_mul_hi_u32 s0, s54, s0
	s_mul_i32 s1, s0, s42
	s_sub_i32 s1, s54, s1
	s_add_i32 s2, s0, 1
	s_sub_i32 s3, s1, s42
	s_cmp_ge_u32 s1, s42
	s_cselect_b32 s0, s2, s0
	s_cselect_b32 s1, s3, s1
	s_add_i32 s2, s0, 1
	s_cmp_ge_u32 s1, s42
	s_cselect_b32 s0, s2, s0
	s_lshr_b32 s1, s54, 1
	s_and_b32 s1, s1, 0x78
	s_or_b32 s1, s1, s52
	s_mul_hi_u32 s2, s1, 0xaaaaaaab
	s_lshr_b32 s4, s2, 3
	s_mul_i32 s2, s4, 12
	s_sub_i32 s5, s1, s2
	s_lshl_b32 s1, s54, 8
	s_and_b32 s1, s1, 0xf00
	s_and_b32 s0, s0, 1
	s_xor_b32 s2, s1, 0xf00
	s_cmp_eq_u32 s0, 0
	s_cselect_b32 s16, s1, s2
	s_lshl_b32 s0, s4, 12
	s_or_b32 s6, s16, s0
	s_lshl_b32 s44, s5, 6
	s_mul_i32 s3, s6, 0x900
	s_mul_hi_u32 s2, s6, 0x900
	s_add_u32 s10, s20, s3
	s_addc_u32 s11, s21, s2
	s_mul_i32 s2, s5, 0x60
	s_mov_b32 s3, s7
	s_lshl_b64 s[2:3], s[2:3], 1
	s_add_u32 s12, s10, s2
	s_addc_u32 s13, s11, s3
	s_mul_i32 s10, s4, 0x900000
	s_mul_hi_u32 s11, s0, 0x900
	s_add_u32 s10, s14, s10
	s_addc_u32 s11, s15, s11
	s_add_u32 s2, s10, s2
	s_addc_u32 s3, s11, s3
	s_mul_i32 s4, s4, 0x600000
	s_mul_hi_u32 s10, s0, 0x600
	s_add_u32 s4, s22, s4
	s_addc_u32 s11, s23, s10
	s_lshl_b32 s5, s5, 7
	s_add_u32 s10, s4, s5
	s_mov_b32 s1, s7
	s_addc_u32 s11, s11, 0
	s_lshr_b32 s4, s16, 6
	s_add_i32 s4, s4, 4
	s_lshl_b64 s[0:1], s[0:1], 2
	s_add_u32 s0, s48, s0
	v_mov_b32_e32 v54, v212
	s_addc_u32 s1, s49, s1
	s_lshl_b32 s5, s16, 2
	s_add_u32 s0, s0, s5
	v_ashrrev_i32_e32 v0, 1, v54
	v_bfi_b32 v216, s27, v0, v54
	s_addc_u32 s1, s1, 0
	v_ashrrev_i32_e32 v217, 31, v216
	v_lshl_add_u64 v[2:3], v[216:217], 2, s[0:1]
	global_load_dword v58, v[2:3], off
	s_waitcnt vmcnt(9)
	v_bfe_u32 v112, v54, 5, 1
	v_lshlrev_b32_e32 v69, 3, v112
	v_cvt_f32_ubyte0_e32 v47, v69
	v_or_b32_e32 v48, 1, v69
	v_cmp_lt_i32_e32 vcc, v227, v228
	v_mul_f32_e32 v49, 0xbf549a78, v47
	v_cvt_f32_ubyte0_e32 v48, v48
	v_cndmask_b32_e32 v2, v226, v227, vcc
	v_cmp_gt_f32_e32 vcc, s38, v49
	v_mul_f32_e32 v50, 0xbf549a78, v48
	v_cmp_gt_f32_e64 s[0:1], s38, v50
	v_cndmask_b32_e32 v49, 0, v232, vcc
	v_fmac_f32_e32 v49, 0xbf549a78, v47
	v_cndmask_b32_e64 v47, 0, v232, s[0:1]
	v_fmac_f32_e32 v47, 0xbf549a78, v48
	v_exp_f32_e32 v47, v47
	v_and_b32_e32 v46, 0xffffffe0, v0
	v_exp_f32_e32 v49, v49
	v_cndmask_b32_e64 v50, 0, v233, s[0:1]
	v_ldexp_f32 v60, v47, v50
	v_add_u32_e32 v236, s16, v46
	v_mov_b64_e32 v[46:47], s[12:13]
	v_lshlrev_b32_e32 v0, 4, v112
	v_mad_i64_i32 v[46:47], s[0:1], v216, s36, v[46:47]
	v_lshlrev_b32_e32 v113, 5, v112
	v_cndmask_b32_e32 v48, 0, v233, vcc
	v_lshl_add_u64 v[56:57], v[46:47], 0, v[0:1]
	v_lshlrev_b32_e32 v235, 2, v2
	global_load_dwordx4 v[42:45], v113, s[80:81]
	global_load_dwordx4 v[38:41], v113, s[80:81] offset:64
	global_load_dwordx4 v[34:37], v113, s[80:81] offset:80
	global_load_dwordx4 v[30:33], v113, s[80:81] offset:128
	global_load_dwordx4 v[26:29], v113, s[80:81] offset:144
	global_load_dwordx4 v[22:25], v113, s[80:81] offset:192
	global_load_dwordx4 v[18:21], v113, s[80:81] offset:208
	global_load_dwordx4 v[14:17], v113, s[80:81] offset:256
	global_load_dwordx4 v[10:13], v113, s[80:81] offset:272
	global_load_dwordx4 v[6:9], v113, s[80:81] offset:320
	global_load_dwordx4 v[2:5], v113, s[80:81] offset:336
	v_ldexp_f32 v59, v49, v48
	global_load_dwordx4 v[50:53], v[56:57], off
	global_load_dwordx4 v[46:49], v[56:57], off offset:32
	global_load_dwordx4 v[102:105], v[56:57], off offset:64
	global_load_dwordx4 v[94:97], v[56:57], off offset:96
	global_load_dwordx4 v[84:87], v[56:57], off offset:128
	global_load_dwordx4 v[88:91], v[56:57], off offset:160
	v_and_b32_e32 v55, 31, v54
	v_ashrrev_i32_e32 v241, 3, v54
	s_lshr_b32 s12, s4, 1
	s_add_i32 s13, s12, -1
	v_or_b32_e32 v237, v236, v55
	s_mov_b32 s45, 3
	v_or_b32_e32 v243, 31, v236
	v_lshlrev_b32_e32 v247, 2, v112
	v_mov_b32_e32 v252, 0xff800000
	v_mov_b32_e32 v253, 0
	s_movk_i32 s53, 0xff
	s_waitcnt vmcnt(17)
	v_cvt_f32_i32_e32 v71, v58
	v_mul_f32_e32 v57, v60, v71
	v_mul_f32_e32 v56, v59, v71
	v_mul_f32_e32 v59, 0.15915494, v57
	v_floor_f32_e32 v59, v59
	v_fma_f32 v59, v57, 0.15915494, -v59
	v_or_b32_e32 v57, 2, v69
	v_cvt_f32_ubyte0_e32 v57, v57
	v_mul_f32_e32 v60, 0xbf549a78, v57
	v_cmp_gt_f32_e32 vcc, s38, v60
	v_mul_f32_e32 v58, 0.15915494, v56
	v_floor_f32_e32 v58, v58
	v_cndmask_b32_e32 v60, 0, v232, vcc
	v_fmac_f32_e32 v60, 0xbf549a78, v57
	v_exp_f32_e32 v60, v60
	v_cndmask_b32_e32 v61, 0, v233, vcc
	v_fma_f32 v58, v56, 0.15915494, -v58
	v_sin_f32_e32 v56, v58
	v_ldexp_f32 v60, v60, v61
	v_mul_f32_e32 v60, v60, v71
	v_mul_f32_e32 v61, 0.15915494, v60
	v_floor_f32_e32 v61, v61
	v_fma_f32 v61, v60, 0.15915494, -v61
	v_or_b32_e32 v60, 3, v69
	v_cvt_f32_ubyte0_e32 v60, v60
	v_mul_f32_e32 v62, 0xbf549a78, v60
	v_cmp_gt_f32_e32 vcc, s38, v62
	s_waitcnt vmcnt(3)
	v_and_b32_e32 v99, 0xffff0000, v104
	v_lshlrev_b32_e32 v98, 16, v104
	v_cndmask_b32_e32 v62, 0, v232, vcc
	v_fmac_f32_e32 v62, 0xbf549a78, v60
	v_exp_f32_e32 v63, v62
	v_sin_f32_e32 v60, v61
	v_cos_f32_e32 v62, v61
	v_cndmask_b32_e32 v61, 0, v233, vcc
	v_ldexp_f32 v61, v63, v61
	v_mul_f32_e32 v61, v61, v71
	v_mul_f32_e32 v63, 0.15915494, v61
	v_floor_f32_e32 v63, v63
	v_fma_f32 v63, v61, 0.15915494, -v63
	v_or_b32_e32 v61, 4, v69
	v_cvt_f32_ubyte0_e32 v61, v61
	v_mul_f32_e32 v64, 0xbf549a78, v61
	v_cmp_gt_f32_e32 vcc, s38, v64
	s_waitcnt vmcnt(1)
	v_and_b32_e32 v75, 0xffff0000, v87
	v_lshlrev_b32_e32 v74, 16, v87
	v_cndmask_b32_e32 v64, 0, v232, vcc
	v_fmac_f32_e32 v64, 0xbf549a78, v61
	v_exp_f32_e32 v64, v64
	v_cndmask_b32_e32 v65, 0, v233, vcc
	s_waitcnt vmcnt(0)
; DI float bf2f(bf16_t v) { return __uint_as_float(((unsigned)v) << 16); }
; template <int DQK, int MODE, bool QN, bool KN> ...
;     ...
;     for (int s = 0; s < NS; ++s)
; #pragma unroll
;       for (int j = 0; j < 8; ++j) { qv[s][j] = bf2f((bf16_t)qf[s][j]); ss += qv[s][j] * qv[s][j]; }
;     ss += __shfl_xor(ss, 32);
;     const float rstd = rsqrtf(ss * (1.f / DQK) + EPS) * oscale;
; #pragma unroll
;     for (int s = 0; s < NS; ++s) {
;       const f32x4 g0 = *(const f32x4*)(gq + 16 * s + 8 * h), g1 = *(const f32x4*)(gq + 16 * s + 8 * h + 4);
; #pragma unroll
;       for (int j = 0; j < 4; ++j) { qv[s][j] *= rstd * g0[j]; qv[s][4 + j] *= rstd * g1[j]; }
;     }
;     if (DQK == 96) {
;       const float pf_ = (float)qpos[wave * 32 + r];
; #pragma unroll
;       for (int j = 0; j < 8; ++j) {
;         const float ang = pf_ * exp2f(-(float)(8 * h + j) * (13.287712379549449f / 16.f));
;         float rev = ang * 0.15915494309189535f; rev = rev - floorf(rev);
;         const float sn = __builtin_amdgcn_sinf(rev), cs = __builtin_amdgcn_cosf(rev);
	v_and_b32_e32 v73, 0xffff0000, v91
	v_and_b32_e32 v81, 0xffff0000, v86
	v_ldexp_f32 v64, v64, v65
	v_mul_f32_e32 v64, v64, v71
	v_mul_f32_e32 v65, 0.15915494, v64
	v_floor_f32_e32 v65, v65
	v_fma_f32 v65, v64, 0.15915494, -v65
	v_or_b32_e32 v64, 5, v69
	v_cvt_f32_ubyte0_e32 v64, v64
	v_mul_f32_e32 v66, 0xbf549a78, v64
	v_cmp_gt_f32_e32 vcc, s38, v66
	v_lshlrev_b32_e32 v80, 16, v86
	v_and_b32_e32 v77, 0xffff0000, v90
	v_cndmask_b32_e32 v66, 0, v232, vcc
	v_fmac_f32_e32 v66, 0xbf549a78, v64
	v_exp_f32_e32 v67, v66
	v_sin_f32_e32 v64, v65
	v_cos_f32_e32 v66, v65
	v_cndmask_b32_e32 v65, 0, v233, vcc
	v_ldexp_f32 v65, v67, v65
	v_mul_f32_e32 v65, v65, v71
	v_mul_f32_e32 v67, 0.15915494, v65
	v_floor_f32_e32 v67, v67
	v_fma_f32 v67, v65, 0.15915494, -v67
	v_or_b32_e32 v65, 6, v69
	v_cvt_f32_ubyte0_e32 v65, v65
	v_or_b32_e32 v69, 7, v69
	v_mul_f32_e32 v68, 0xbf549a78, v65
	v_cvt_f32_ubyte0_e32 v69, v69
	v_cmp_gt_f32_e32 vcc, s38, v68
	v_mul_f32_e32 v72, 0xbf549a78, v69
	v_lshlrev_b32_e32 v76, 16, v90
	v_cndmask_b32_e32 v68, 0, v232, vcc
	v_cndmask_b32_e32 v70, 0, v233, vcc
	v_cmp_gt_f32_e32 vcc, s38, v72
	v_and_b32_e32 v83, 0xffff0000, v85
	v_lshlrev_b32_e32 v82, 16, v85
	v_cndmask_b32_e32 v72, 0, v232, vcc
	v_fmac_f32_e32 v72, 0xbf549a78, v69
	v_exp_f32_e32 v69, v72
	v_lshlrev_b32_e32 v72, 16, v91
	v_and_b32_e32 v79, 0xffff0000, v89
	v_lshlrev_b32_e32 v78, 16, v89
	v_and_b32_e32 v87, 0xffff0000, v84
	v_lshlrev_b32_e32 v86, 16, v84
	v_and_b32_e32 v85, 0xffff0000, v88
	v_lshlrev_b32_e32 v84, 16, v88
	v_and_b32_e32 v89, 0xffff0000, v97
	v_lshlrev_b32_e32 v88, 16, v97
	v_and_b32_e32 v91, 0xffff0000, v96
	v_lshlrev_b32_e32 v90, 16, v96
	v_and_b32_e32 v97, 0xffff0000, v105
	v_lshlrev_b32_e32 v96, 16, v105
	v_and_b32_e32 v105, 0xffff0000, v49
	v_lshlrev_b32_e32 v104, 16, v49
	v_and_b32_e32 v107, 0xffff0000, v48
	v_lshlrev_b32_e32 v106, 16, v48
	v_and_b32_e32 v109, 0xffff0000, v47
	v_lshlrev_b32_e32 v108, 16, v47
	v_and_b32_e32 v111, 0xffff0000, v46
	v_lshlrev_b32_e32 v110, 16, v46
	global_load_dwordx4 v[46:49], v113, s[80:81] offset:16
	v_and_b32_e32 v165, 0xffff0000, v50
	v_lshlrev_b32_e32 v164, 16, v50
	v_and_b32_e32 v161, 0xffff0000, v51
	v_lshlrev_b32_e32 v160, 16, v51
	v_pk_mul_f32 v[50:51], v[164:165], v[164:165]
	v_pk_mul_f32 v[162:163], v[160:161], v[160:161]
	v_add_f32_e32 v50, v50, v51
	v_and_b32_e32 v159, 0xffff0000, v52
	v_lshlrev_b32_e32 v158, 16, v52
	v_add_f32_e32 v50, v162, v50
	v_and_b32_e32 v155, 0xffff0000, v53
	v_lshlrev_b32_e32 v154, 16, v53
	v_pk_mul_f32 v[52:53], v[158:159], v[158:159]
	v_add_f32_e32 v50, v163, v50
	v_add_f32_e32 v50, v52, v50
	v_pk_mul_f32 v[156:157], v[154:155], v[154:155]
	v_add_f32_e32 v50, v53, v50
	v_add_f32_e32 v50, v156, v50
	v_pk_mul_f32 v[152:153], v[110:111], v[110:111]
	v_add_f32_e32 v50, v157, v50
	v_add_f32_e32 v50, v152, v50
	v_pk_mul_f32 v[150:151], v[108:109], v[108:109]
	v_add_f32_e32 v50, v153, v50
	v_add_f32_e32 v50, v150, v50
	v_pk_mul_f32 v[148:149], v[106:107], v[106:107]
	v_add_f32_e32 v50, v151, v50
	v_add_f32_e32 v50, v148, v50
	v_pk_mul_f32 v[146:147], v[104:105], v[104:105]
	v_add_f32_e32 v50, v149, v50
	v_and_b32_e32 v101, 0xffff0000, v103
	v_lshlrev_b32_e32 v100, 16, v103
	v_and_b32_e32 v103, 0xffff0000, v102
	v_lshlrev_b32_e32 v102, 16, v102
	v_add_f32_e32 v50, v146, v50
	v_pk_mul_f32 v[144:145], v[102:103], v[102:103]
	v_add_f32_e32 v50, v147, v50
	v_add_f32_e32 v50, v144, v50
	v_pk_mul_f32 v[142:143], v[100:101], v[100:101]
	v_add_f32_e32 v50, v145, v50
	v_add_f32_e32 v50, v142, v50
	v_pk_mul_f32 v[140:141], v[98:99], v[98:99]
	v_add_f32_e32 v50, v143, v50
	v_add_f32_e32 v50, v140, v50
	v_pk_mul_f32 v[138:139], v[96:97], v[96:97]
	v_add_f32_e32 v50, v141, v50
	v_and_b32_e32 v93, 0xffff0000, v95
	v_lshlrev_b32_e32 v92, 16, v95
	v_and_b32_e32 v95, 0xffff0000, v94
	v_lshlrev_b32_e32 v94, 16, v94
	v_add_f32_e32 v50, v138, v50
	v_pk_mul_f32 v[136:137], v[94:95], v[94:95]
	v_add_f32_e32 v50, v139, v50
	v_add_f32_e32 v50, v136, v50
	v_pk_mul_f32 v[134:135], v[92:93], v[92:93]
	v_add_f32_e32 v50, v137, v50
	v_add_f32_e32 v50, v134, v50
	v_pk_mul_f32 v[132:133], v[90:91], v[90:91]
	v_add_f32_e32 v50, v135, v50
	v_add_f32_e32 v50, v132, v50
	v_pk_mul_f32 v[130:131], v[88:89], v[88:89]
	v_add_f32_e32 v50, v133, v50
	v_add_f32_e32 v50, v130, v50
	v_pk_mul_f32 v[126:127], v[86:87], v[86:87]
	v_add_f32_e32 v50, v131, v50
	v_add_f32_e32 v50, v126, v50
	v_pk_mul_f32 v[122:123], v[82:83], v[82:83]
	v_add_f32_e32 v50, v127, v50
	v_add_f32_e32 v50, v122, v50
	v_pk_mul_f32 v[118:119], v[80:81], v[80:81]
	v_add_f32_e32 v50, v123, v50
	v_add_f32_e32 v50, v118, v50
	v_pk_mul_f32 v[114:115], v[74:75], v[74:75]
	v_add_f32_e32 v50, v119, v50
	v_add_f32_e32 v50, v114, v50
	v_pk_mul_f32 v[128:129], v[84:85], v[84:85]
	v_add_f32_e32 v50, v115, v50
	v_add_f32_e32 v50, v128, v50
	v_pk_mul_f32 v[124:125], v[78:79], v[78:79]
	v_add_f32_e32 v50, v129, v50
	v_add_f32_e32 v50, v124, v50
	v_pk_mul_f32 v[120:121], v[76:77], v[76:77]
	v_add_f32_e32 v50, v125, v50
	v_add_f32_e32 v50, v120, v50
	v_pk_mul_f32 v[116:117], v[72:73], v[72:73]
	v_add_f32_e32 v50, v121, v50
	v_add_f32_e32 v50, v116, v50
	v_add_f32_e32 v50, v117, v50
	ds_bpermute_b32 v51, v235, v50
	v_fmac_f32_e32 v68, 0xbf549a78, v65
	v_cndmask_b32_e32 v166, 0, v233, vcc
	v_exp_f32_e32 v68, v68
	v_ldexp_f32 v52, v69, v166
	s_waitcnt lgkmcnt(0)
; DI unsigned pack2(float a, float b) { bf2_t v = __builtin_convertvector((f32x2){a, b}, bf2_t); return __builtin_bit_cast(unsigned, v); }
; template <int DQK, int MODE, bool QN, bool KN> ...
;     ...
;     ss += __shfl_xor(ss, 32);
;     const float rstd = rsqrtf(ss * (1.f / DQK) + EPS) * oscale;
; #pragma unroll
;     for (int s = 0; s < NS; ++s) {
;       const f32x4 g0 = *(const f32x4*)(gq + 16 * s + 8 * h), g1 = *(const f32x4*)(gq + 16 * s + 8 * h + 4);
; #pragma unroll
;       for (int j = 0; j < 4; ++j) { qv[s][j] *= rstd * g0[j]; qv[s][4 + j] *= rstd * g1[j]; }
;     }
;     if (DQK == 96) {
;       const float pf_ = (float)qpos[wave * 32 + r];
; #pragma unroll
;       for (int j = 0; j < 8; ++j) {
;         const float ang = pf_ * exp2f(-(float)(8 * h + j) * (13.287712379549449f / 16.f));
;         float rev = ang * 0.15915494309189535f; rev = rev - floorf(rev);
;         const float sn = __builtin_amdgcn_sinf(rev), cs = __builtin_amdgcn_cosf(rev);
;         const float x1 = qv[NS - 2][j], x2 = qv[NS - 1][j];
;         qv[NS - 2][j] = x1 * cs - x2 * sn; qv[NS - 1][j] = x2 * cs + x1 * sn;
;       }
;     }
; #pragma unroll
;     for (int s = 0; s < NS; ++s) {
;       u32x4 w; w.x = pack2(qv[s][0], qv[s][1]); w.y = pack2(qv[s][2], qv[s][3]); w.z = pack2(qv[s][4], qv[s][5]); w.w = pack2(qv[s][6], qv[s][7]);
;       qf[s] = __builtin_bit_cast(bf16x8, w);
;     }
;   }
;   f32x4 gk0 = {1.f, 1.f, 1.f, 1.f}, gk1 = {1.f, 1.f, 1.f, 1.f};
;   if (KN) { gk0 = *(const f32x4*)(gk + (tid & 7) * 8); gk1 = *(const f32x4*)(gk + (tid & 7) * 8 + 4); }
;   float sbound = 0.f; bool fixed_shift = false;
;   if (MODE != 2 && QN) {
;     float gqm = 0.f, gkm = 0.f;
; #pragma unroll
;     for (int s = 0; s < NS; ++s)
; #pragma unroll
;       for (int j = 0; j < 8; ++j) { gqm = fmaxf(gqm, fabsf(gq[16 * s + 8 * h + j])); gkm = fmaxf(gkm, fabsf(gk[16 * s + 8 * h + j])); }
;     gqm = fmaxf(gqm, __shfl_xor(gqm, 32)); gkm = fmaxf(gkm, __shfl_xor(gkm, 32));
;     sbound = sqrtf((float)DQK) * 1.4426950408889634f * gqm * gkm * 1.02f + 0.01f;
;     fixed_shift = __builtin_amdgcn_readfirstlane(sbound < 48.f ? 1 : 0) != 0;
	v_add_f32_e32 v50, v50, v51
	v_fmamk_f32 v50, v50, 0x3c2aaaab, v214
	v_mul_f32_e32 v51, 0x4b800000, v50
	v_cmp_gt_f32_e32 vcc, s28, v50
	v_mul_f32_e32 v52, v52, v71
	v_mul_f32_e32 v53, 0.15915494, v52
	v_cndmask_b32_e32 v50, v50, v51, vcc
	v_rsq_f32_e32 v50, v50
	v_floor_f32_e32 v53, v53
	v_ldexp_f32 v68, v68, v70
	v_fma_f32 v51, v52, 0.15915494, -v53
	v_mul_f32_e32 v68, v68, v71
	v_sin_f32_e32 v69, v51
	v_cos_f32_e32 v71, v51
	v_mul_f32_e32 v51, 0x45800000, v50
	v_cndmask_b32_e32 v50, v50, v51, vcc
	v_mul_f32_e32 v126, 0x3e16c672, v50
	global_load_dwordx4 v[50:53], v113, s[82:83]
	v_pk_mul_f32 v[114:115], v[42:43], v[126:127] op_sel_hi:[1,0]
	s_waitcnt vmcnt(1)
	v_pk_mul_f32 v[118:119], v[46:47], v[126:127] op_sel_hi:[1,0]
	v_pk_mul_f32 v[128:129], v[114:115], v[164:165]
	global_load_dwordx4 v[114:117], v113, s[82:83] offset:16
	v_pk_mul_f32 v[130:131], v[118:119], v[158:159]
	v_pk_mul_f32 v[118:119], v[44:45], v[126:127] op_sel_hi:[1,0]
	v_pk_mul_f32 v[122:123], v[38:39], v[126:127] op_sel_hi:[1,0]
	v_pk_mul_f32 v[132:133], v[118:119], v[160:161]
	v_pk_mul_f32 v[118:119], v[48:49], v[126:127] op_sel_hi:[1,0]
	v_pk_mul_f32 v[136:137], v[122:123], v[110:111]
	v_pk_mul_f32 v[134:135], v[118:119], v[154:155]
	global_load_dwordx4 v[118:121], v113, s[82:83] offset:64
	v_pk_mul_f32 v[110:111], v[34:35], v[126:127] op_sel_hi:[1,0]
	global_load_dwordx4 v[122:125], v113, s[82:83] offset:80
	v_pk_mul_f32 v[138:139], v[110:111], v[106:107]
	v_pk_mul_f32 v[106:107], v[40:41], v[126:127] op_sel_hi:[1,0]
	v_max3_f32 v42, |v42|, 0, |v43|
	v_pk_mul_f32 v[140:141], v[106:107], v[108:109]
	v_pk_mul_f32 v[106:107], v[36:37], v[126:127] op_sel_hi:[1,0]
	v_pk_mul_f32 v[108:109], v[30:31], v[126:127] op_sel_hi:[1,0]
	v_pk_mul_f32 v[142:143], v[106:107], v[104:105]
	global_load_dwordx4 v[104:107], v113, s[82:83] offset:128
	v_pk_mul_f32 v[144:145], v[108:109], v[102:103]
	v_pk_mul_f32 v[102:103], v[26:27], v[126:127] op_sel_hi:[1,0]
	global_load_dwordx4 v[108:111], v113, s[82:83] offset:144
	v_pk_mul_f32 v[146:147], v[102:103], v[98:99]
	v_pk_mul_f32 v[98:99], v[32:33], v[126:127] op_sel_hi:[1,0]
	v_max3_f32 v42, v42, |v44|, |v45|
	v_pk_mul_f32 v[148:149], v[98:99], v[100:101]
	v_pk_mul_f32 v[98:99], v[28:29], v[126:127] op_sel_hi:[1,0]
	v_pk_mul_f32 v[100:101], v[22:23], v[126:127] op_sel_hi:[1,0]
	v_pk_mul_f32 v[150:151], v[98:99], v[96:97]
	global_load_dwordx4 v[96:99], v113, s[82:83] offset:192
	v_pk_mul_f32 v[152:153], v[100:101], v[94:95]
	v_pk_mul_f32 v[94:95], v[18:19], v[126:127] op_sel_hi:[1,0]
	global_load_dwordx4 v[100:103], v113, s[82:83] offset:208
	v_pk_mul_f32 v[154:155], v[94:95], v[90:91]
	v_pk_mul_f32 v[90:91], v[24:25], v[126:127] op_sel_hi:[1,0]
	v_max3_f32 v42, v42, |v46|, |v47|
	v_pk_mul_f32 v[156:157], v[90:91], v[92:93]
	v_pk_mul_f32 v[90:91], v[20:21], v[126:127] op_sel_hi:[1,0]
	v_pk_mul_f32 v[92:93], v[14:15], v[126:127] op_sel_hi:[1,0]
	v_pk_mul_f32 v[158:159], v[90:91], v[88:89]
	global_load_dwordx4 v[88:91], v113, s[82:83] offset:256
	v_pk_mul_f32 v[160:161], v[92:93], v[86:87]
	v_pk_mul_f32 v[86:87], v[10:11], v[126:127] op_sel_hi:[1,0]
	global_load_dwordx4 v[92:95], v113, s[82:83] offset:272
	v_pk_mul_f32 v[162:163], v[86:87], v[80:81]
	v_pk_mul_f32 v[80:81], v[16:17], v[126:127] op_sel_hi:[1,0]
	v_pk_mul_f32 v[86:87], v[6:7], v[126:127] op_sel_hi:[1,0]
	v_pk_mul_f32 v[164:165], v[80:81], v[82:83]
	v_pk_mul_f32 v[80:81], v[12:13], v[126:127] op_sel_hi:[1,0]
	v_pk_mul_f32 v[166:167], v[86:87], v[84:85]
	v_pk_mul_f32 v[74:75], v[80:81], v[74:75]
	global_load_dwordx4 v[80:83], v113, s[82:83] offset:320
	global_load_dwordx4 v[84:87], v113, s[82:83] offset:336
	v_max3_f32 v42, v42, |v48|, |v49|
	v_max3_f32 v38, v42, |v38|, |v39|
	v_max3_f32 v38, v38, |v40|, |v41|
	v_max3_f32 v34, v38, |v34|, |v35|
	v_max3_f32 v34, v34, |v36|, |v37|
	v_max3_f32 v30, v34, |v30|, |v31|
	v_max3_f32 v30, v30, |v32|, |v33|
	v_max3_f32 v26, v30, |v26|, |v27|
	v_max3_f32 v26, v26, |v28|, |v29|
	v_max3_f32 v22, v26, |v22|, |v23|
	v_max3_f32 v22, v22, |v24|, |v25|
	v_max3_f32 v18, v22, |v18|, |v19|
	v_max3_f32 v18, v18, |v20|, |v21|
	v_max3_f32 v14, v18, |v14|, |v15|
	v_max3_f32 v48, v14, |v16|, |v17|
	v_max3_f32 v10, v48, |v10|, |v11|
	v_max3_f32 v10, v10, |v12|, |v13|
	v_max3_f32 v6, v10, |v6|, |v7|
	v_max3_f32 v6, v6, |v8|, |v9|
	v_pk_mul_f32 v[168:169], v[2:3], v[126:127] op_sel_hi:[1,0]
	v_max3_f32 v2, v6, |v2|, |v3|
	v_max3_f32 v2, v2, |v4|, |v5|
	v_pk_mul_f32 v[76:77], v[168:169], v[76:77]
	s_waitcnt vmcnt(11)
	v_max3_f32 v43, |v50|, 0, |v51|
	v_max3_f32 v43, v43, |v52|, |v53|
	v_pk_mul_f32 v[168:169], v[8:9], v[126:127] op_sel_hi:[1,0]
	v_pk_mul_f32 v[126:127], v[4:5], v[126:127] op_sel_hi:[1,0]
	s_waitcnt vmcnt(10)
	v_max3_f32 v43, v43, |v114|, |v115|
	v_max3_f32 v43, v43, |v116|, |v117|
	v_mul_hi_i32 v14, v54, s39
	ds_bpermute_b32 v4, v235, v2
	v_add_u32_e32 v34, 0x200, v54
	v_add_u32_e32 v26, 0x400, v54
	v_lshlrev_b32_e32 v50, 4, v54
	v_and_b32_e32 v30, 0x70, v50
	s_waitcnt vmcnt(9)
	v_max3_f32 v39, v43, |v118|, |v119|
	v_max3_f32 v39, v39, |v120|, |v121|
	s_waitcnt vmcnt(8)
	v_max3_f32 v35, v39, |v122|, |v123|
	v_max3_f32 v35, v35, |v124|, |v125|
	s_waitcnt lgkmcnt(0)
	v_max_f32_e32 v4, v4, v4
	v_max_f32_e32 v2, v2, v4
	v_mul_f32_e32 v2, 0x41622ae0, v2
	v_mov_b64_e32 v[16:17], s[2:3]
	v_ashrrev_i32_e32 v242, 3, v34
	v_sin_f32_e32 v57, v59
	s_waitcnt vmcnt(7)
	v_max3_f32 v31, v35, |v104|, |v105|
	v_max3_f32 v31, v31, |v106|, |v107|
	v_cos_f32_e32 v58, v58
	s_waitcnt vmcnt(6)
	v_max3_f32 v27, v31, |v108|, |v109|
	v_max3_f32 v27, v27, |v110|, |v111|
	v_mov_b32_e32 v31, v1
	v_lshl_add_u64 v[218:219], s[10:11], 0, v[30:31]
	v_mad_i64_i32 v[30:31], s[0:1], v241, s37, v[218:219]
	v_cos_f32_e32 v59, v59
	v_sin_f32_e32 v61, v63
	s_waitcnt vmcnt(5)
; DI unsigned pack2(float a, float b) { bf2_t v = __builtin_convertvector((f32x2){a, b}, bf2_t); return __builtin_bit_cast(unsigned, v); }
; template <int DQK, int MODE, bool QN, bool KN> ...
;     ...
;         const float ang = pf_ * exp2f(-(float)(8 * h + j) * (13.287712379549449f / 16.f));
;         float rev = ang * 0.15915494309189535f; rev = rev - floorf(rev);
;         const float sn = __builtin_amdgcn_sinf(rev), cs = __builtin_amdgcn_cosf(rev);
;         const float x1 = qv[NS - 2][j], x2 = qv[NS - 1][j];
;         qv[NS - 2][j] = x1 * cs - x2 * sn; qv[NS - 1][j] = x2 * cs + x1 * sn;
;       }
;     }
; #pragma unroll
;     for (int s = 0; s < NS; ++s) {
;       u32x4 w; w.x = pack2(qv[s][0], qv[s][1]); w.y = pack2(qv[s][2], qv[s][3]); w.z = pack2(qv[s][4], qv[s][5]); w.w = pack2(qv[s][6], qv[s][7]);
;       qf[s] = __builtin_bit_cast(bf16x8, w);
;     }
;   }
;   f32x4 gk0 = {1.f, 1.f, 1.f, 1.f}, gk1 = {1.f, 1.f, 1.f, 1.f};
;   if (KN) { gk0 = *(const f32x4*)(gk + (tid & 7) * 8); gk1 = *(const f32x4*)(gk + (tid & 7) * 8 + 4); }
;   float sbound = 0.f; bool fixed_shift = false;
;   if (MODE != 2 && QN) {
;     float gqm = 0.f, gkm = 0.f;
; #pragma unroll
;     for (int s = 0; s < NS; ++s)
; #pragma unroll
;       for (int j = 0; j < 8; ++j) { gqm = fmaxf(gqm, fabsf(gq[16 * s + 8 * h + j])); gkm = fmaxf(gkm, fabsf(gk[16 * s + 8 * h + j])); }
;     gqm = fmaxf(gqm, __shfl_xor(gqm, 32)); gkm = fmaxf(gkm, __shfl_xor(gkm, 32));
;     sbound = sqrtf((float)DQK) * 1.4426950408889634f * gqm * gkm * 1.02f + 0.01f;
;     fixed_shift = __builtin_amdgcn_readfirstlane(sbound < 48.f ? 1 : 0) != 0;
;   }
;   f32x16 o[2];
; #pragma unroll
;   for (int a = 0; a < 2; ++a)
; #pragma unroll
;     for (int i = 0; i < 16; ++i) o[a][i] = 0.f;
;   float m_run = -INFINITY, l_run = 0.f, carry = 1.f;
;   u32x4 rk0[NKL], rv0[2], rk1[NKL], rv1[2];
;   const int vtr_off = (4 * h + ((lane & 15) >> 2)) * 64 + (((lane >> 4) & 1) * 16 + 4 * (lane & 3)) * 2;
;     ...
;   const int nsg = nkt >> 1;
;   auto tile_of = [&](int it) { return MODE == 2 ? (nkt - 1 - it) : it; };
;   auto stage_key0 = [&](int sg) { const int sc = sg < nsg ? sg : nsg - 1; return 128 * (MODE == 2 ? (nsg - 1 - sc) : sc); };
;   AT_GLOAD(rk0, rv0, 0)
;   AT_GLOAD(rk1, rv1, 1)
	v_max3_f32 v23, v27, |v96|, |v97|
	v_max3_f32 v23, v23, |v98|, |v99|
	v_cos_f32_e32 v63, v63
	s_waitcnt vmcnt(4)
	v_max3_f32 v19, v23, |v100|, |v101|
	v_max3_f32 v19, v19, |v102|, |v103|
	v_mul_f32_e32 v70, 0.15915494, v68
	v_sin_f32_e32 v65, v67
	v_floor_f32_e32 v70, v70
	v_pk_mul_f32 v[72:73], v[126:127], v[72:73]
	v_pk_mul_f32 v[126:127], v[56:57], v[166:167]
	v_cos_f32_e32 v67, v67
	s_waitcnt vmcnt(3)
	v_max3_f32 v15, v19, |v88|, |v89|
	v_max3_f32 v49, v15, |v90|, |v91|
	v_lshrrev_b32_e32 v15, 31, v14
	s_waitcnt vmcnt(2)
	v_max3_f32 v11, v49, |v92|, |v93|
	v_max3_f32 v11, v11, |v94|, |v95|
	v_ashrrev_i32_e32 v14, 1, v14
	v_add_u32_e32 v238, v14, v15
	v_mad_u64_u32 v[14:15], s[0:1], v238, -12, v[54:55]
	v_lshlrev_b32_e32 v20, 3, v14
	v_ashrrev_i32_e32 v21, 31, v20
	s_waitcnt vmcnt(1)
	v_max3_f32 v7, v11, |v80|, |v81|
	v_max3_f32 v7, v7, |v82|, |v83|
	s_waitcnt vmcnt(0)
	v_max3_f32 v3, v7, |v84|, |v85|
	v_max3_f32 v3, v3, |v86|, |v87|
	ds_bpermute_b32 v5, v235, v3
	v_mul_hi_i32 v15, v34, s39
	v_lshlrev_b64 v[38:39], 1, v[20:21]
	v_lshrrev_b32_e32 v20, 31, v15
	v_ashrrev_i32_e32 v15, 1, v15
	s_waitcnt lgkmcnt(0)
	v_max_f32_e32 v4, v5, v5
	v_add_u32_e32 v239, v15, v20
	v_mul_hi_i32 v15, v26, s39
	v_max_f32_e32 v3, v3, v4
	v_lshrrev_b32_e32 v27, 31, v15
	v_ashrrev_i32_e32 v15, 1, v15
	v_mul_f32_e32 v2, v2, v3
	v_add_u32_e32 v240, v15, v27
	v_fmamk_f32 v6, v2, 0x3f828f5c, v215
	v_mad_u64_u32 v[40:41], s[0:1], v239, -12, v[34:35]
	v_mad_u64_u32 v[44:45], s[0:1], v240, -12, v[26:27]
	v_cmp_gt_f32_e32 vcc, s29, v6
	v_mad_i64_i32 v[18:19], s[0:1], v238, s36, v[16:17]
	v_mad_i64_i32 v[20:21], s[0:1], v239, s36, v[16:17]
	v_lshlrev_b32_e32 v22, 3, v40
	v_mad_i64_i32 v[26:27], s[0:1], v240, s36, v[16:17]
	v_lshlrev_b32_e32 v28, 3, v44
	v_mad_i64_i32 v[34:35], s[0:1], v242, s37, v[218:219]
	v_cndmask_b32_e64 v2, 0, 1, vcc
	v_ashrrev_i32_e32 v23, 31, v22
	v_ashrrev_i32_e32 v29, 31, v28
	v_readfirstlane_b32 s0, v2
	v_add_u32_e32 v2, 0x80, v238
	v_lshlrev_b64 v[42:43], 1, v[22:23]
	v_lshlrev_b64 v[46:47], 1, v[28:29]
	s_bitcmp1_b32 s0, 0
	v_mad_i64_i32 v[2:3], s[0:1], v2, s36, v[16:17]
	v_lshl_add_u64 v[18:19], v[18:19], 0, v[38:39]
	v_lshl_add_u64 v[22:23], v[20:21], 0, v[42:43]
	v_lshl_add_u64 v[26:27], v[26:27], 0, v[46:47]
	v_lshl_add_u64 v[2:3], v[2:3], 0, v[38:39]
	global_load_dwordx4 v[18:21], v[18:19], off
	s_nop 0
	global_load_dwordx4 v[22:25], v[22:23], off
	v_add_u32_e32 v4, 0x80, v240
	global_load_dwordx4 v[26:29], v[26:27], off
	v_mad_i64_i32 v[4:5], s[0:1], v4, s36, v[16:17]
	global_load_dwordx4 v[184:187], v[2:3], off
	v_add_u32_e32 v2, 0x80, v239
	v_mad_i64_i32 v[2:3], s[0:1], v2, s36, v[16:17]
	global_load_dwordx4 v[30:33], v[30:31], off
	v_lshl_add_u64 v[2:3], v[2:3], 0, v[42:43]
	global_load_dwordx4 v[34:37], v[34:35], off
	v_lshl_add_u64 v[4:5], v[4:5], 0, v[46:47]
	global_load_dwordx4 v[188:191], v[2:3], off
	global_load_dwordx4 v[192:195], v[4:5], off
	v_add_u32_e32 v2, 0x80, v241
	v_mad_i64_i32 v[2:3], s[0:1], v2, s37, v[218:219]
	v_add_u32_e32 v4, 0x80, v242
	v_mad_i64_i32 v[4:5], s[0:1], v4, s37, v[218:219]
	global_load_dwordx4 v[196:199], v[2:3], off
	global_load_dwordx4 v[200:203], v[4:5], off
	v_mul_lo_u32 v2, v238, s40
	v_add_u32_e32 v2, 0x110, v2
	v_lshlrev_b32_e32 v3, 4, v14
	v_add_u32_e32 v244, v2, v3
	v_mul_lo_u32 v2, v239, s40
	v_add_u32_e32 v2, 0x110, v2
	v_lshlrev_b32_e32 v3, 4, v40
	v_fma_f32 v70, v68, 0.15915494, -v70
	v_pk_mul_f32 v[78:79], v[168:169], v[78:79]
	v_pk_fma_f32 v[126:127], v[58:59], v[160:161], v[126:127] neg_lo:[0,0,1] neg_hi:[0,0,1]
	v_pk_mul_f32 v[58:59], v[58:59], v[166:167]
	v_add_u32_e32 v245, v2, v3
	v_mul_lo_u32 v2, v240, s40
	v_sin_f32_e32 v68, v70
	v_pk_fma_f32 v[56:57], v[56:57], v[160:161], v[58:59]
	v_pk_mul_f32 v[58:59], v[60:61], v[78:79]
	v_add_u32_e32 v2, 0x110, v2
	v_lshlrev_b32_e32 v3, 4, v44
	v_cos_f32_e32 v70, v70
	v_pk_fma_f32 v[58:59], v[62:63], v[164:165], v[58:59] neg_lo:[0,0,1] neg_hi:[0,0,1]
	v_pk_mul_f32 v[62:63], v[62:63], v[78:79]
	v_add_u32_e32 v246, v2, v3
	v_lshlrev_b32_e32 v2, 11, v54
	v_pk_fma_f32 v[60:61], v[60:61], v[164:165], v[62:63]
	v_pk_mul_f32 v[62:63], v[64:65], v[76:77]
	v_lshlrev_b32_e32 v7, 3, v54
	s_cselect_b64 s[0:1], -1, 0
	v_and_b32_e32 v2, 0x2000, v2
	v_and_b32_e32 v3, 48, v50
	v_pk_fma_f32 v[62:63], v[66:67], v[162:163], v[62:63] neg_lo:[0,0,1] neg_hi:[0,0,1]
	v_pk_mul_f32 v[66:67], v[66:67], v[76:77]
	v_cndmask_b32_e64 v16, 0, -v6, s[0:1]
	v_add3_u32 v4, s34, v2, v3
	v_and_b32_e32 v40, 0xffffffc0, v7
	v_lshlrev_b32_e32 v6, 2, v54
	v_and_b32_e32 v7, 16, v54
	v_pk_fma_f32 v[64:65], v[64:65], v[162:163], v[66:67]
	v_pk_mul_f32 v[66:67], v[68:69], v[72:73]
	v_add_u32_e32 v248, v4, v40
	v_and_or_b32 v6, v6, 12, v7
	v_pk_fma_f32 v[66:67], v[70:71], v[74:75], v[66:67] neg_lo:[0,0,1] neg_hi:[0,0,1]
	v_pk_mul_f32 v[70:71], v[70:71], v[72:73]
	v_lshlrev_b32_e32 v4, 8, v112
	v_and_b32_e32 v5, 0xc0, v50
	v_lshlrev_b32_e32 v6, 1, v6
	v_mov_b32_e32 v14, v1
	v_mov_b32_e32 v15, v1
	v_pk_fma_f32 v[68:69], v[68:69], v[74:75], v[70:71]
	v_cvt_pk_bf16_f32 v177, v58, v59
	v_cvt_pk_bf16_f32 v178, v62, v63
	v_cvt_pk_bf16_f32 v180, v56, v57
	v_cvt_pk_bf16_f32 v181, v60, v61
	v_or3_b32 v249, v4, v5, v6
	v_lshl_add_u64 v[220:221], s[2:3], 0, v[38:39]
	v_lshl_add_u64 v[222:223], s[2:3], 0, v[42:43]
	v_lshl_add_u64 v[224:225], s[2:3], 0, v[46:47]
	v_mov_b32_e32 v4, v1
	v_mov_b32_e32 v5, v1
	s_waitcnt vmcnt(9)
; DI unsigned pack2(float a, float b) { bf2_t v = __builtin_convertvector((f32x2){a, b}, bf2_t); return __builtin_bit_cast(unsigned, v); }
; #define MFMA32(a, b, c) __builtin_amdgcn_mfma_f32_32x32x16_bf16((a), (b), (c), 0, 0, 0)
; template <int DQK, int MODE, bool QN, bool KN> ...
;     ...
;   AT_GLOAD(rk0, rv0, 0)
;   AT_GLOAD(rk1, rv1, 1)
;   AT_SWRITE(rk0, rv0, 0)
;   __syncthreads();
;   auto compute = [&](int it, int bufi) {
;     const int kt = tile_of(it);
;     const int koff = (kt & 1) * 64;
;     const char* sK = smem + bufi * BUF + koff * KROW;
;     const char* sV = smem + bufi * BUF + KBYTES + koff * 64;
;     bool active = (MODE == 0) || (kt * 64 <= qwmax);
;     if (MODE == 2 && active) active = __builtin_amdgcn_ballot_w64(carry >= 1.17549435e-38f) != 0;
;     if (active) {
;       f32x16 sacc[2];
;       const float sinit = fixed_shift ? -sbound : 0.f;
; #pragma unroll
;       for (int kb = 0; kb < 2; ++kb) {
; #pragma unroll
;         for (int i = 0; i < 16; ++i) sacc[kb][i] = sinit;
;     ...
; #pragma unroll
;       for (int kb = 0; kb < 2; ++kb)
; #pragma unroll
;         for (int s2 = 0; s2 < 2; ++s2) {
;           u32x4 pw;
;           pw.x = pack2(sacc[kb][8 * s2 + 0], sacc[kb][8 * s2 + 1]); pw.y = pack2(sacc[kb][8 * s2 + 2], sacc[kb][8 * s2 + 3]);
;           pw.z = pack2(sacc[kb][8 * s2 + 4], sacc[kb][8 * s2 + 5]); pw.w = pack2(sacc[kb][8 * s2 + 6], sacc[kb][8 * s2 + 7]);
;           const bf16x8 pf = __builtin_bit_cast(bf16x8, pw);
; #pragma unroll
;           for (int dvb = 0; dvb < 2; ++dvb) {
;             const char* vb = sV + dvb * VIMG + (kb * 32 + 16 * s2) * 64 + vtr_off;
;             const s16x4 v0 = tr_read(vb), v1 = tr_read(vb + 8 * 64);
;             const bf16x8 vf = __builtin_shufflevector(v0, v1, 0, 1, 2, 3, 4, 5, 6, 7);
;             o[dvb] = MFMA32(vf, pf, o[dvb]);
;           }
;         }
	ds_write_b128 v244, v[18:21]
	s_waitcnt vmcnt(8)
	ds_write_b128 v245, v[22:25]
	v_mov_b32_e32 v6, v1
	s_waitcnt vmcnt(7)
	ds_write_b128 v246, v[26:29]
	s_waitcnt vmcnt(5)
	ds_write_b128 v248, v[30:33] offset:26624
	s_waitcnt vmcnt(4)
	ds_write_b128 v248, v[34:37] offset:30720
	v_add_u32_e32 v32, 0x110, v0
	v_mul_u32_u24_e32 v33, 0xd0, v55
	v_add3_u32 v34, s41, v2, v3
	v_mov_b32_e32 v0, v1
	v_mov_b32_e32 v2, v1
	v_mov_b32_e32 v3, v1
	v_mov_b32_e32 v7, v1
	v_mov_b32_e32 v8, v1
	v_mov_b32_e32 v9, v1
	v_mov_b32_e32 v10, v1
	v_mov_b32_e32 v11, v1
	v_mov_b32_e32 v12, v1
	v_mov_b32_e32 v13, v1
	v_add_u32_e32 v250, v34, v40
	v_add_u32_e32 v251, v32, v33
	v_mov_b64_e32 v[46:47], v[14:15]
	v_mov_b64_e32 v[62:63], v[14:15]
	v_cvt_pk_bf16_f32 v160, v128, v129
	v_cvt_pk_bf16_f32 v161, v132, v133
	v_cvt_pk_bf16_f32 v162, v130, v131
	v_cvt_pk_bf16_f32 v163, v134, v135
	v_cvt_pk_bf16_f32 v164, v136, v137
	v_cvt_pk_bf16_f32 v165, v140, v141
	v_cvt_pk_bf16_f32 v166, v138, v139
	v_cvt_pk_bf16_f32 v167, v142, v143
	v_cvt_pk_bf16_f32 v168, v144, v145
	v_cvt_pk_bf16_f32 v169, v148, v149
	v_cvt_pk_bf16_f32 v170, v146, v147
	v_cvt_pk_bf16_f32 v171, v150, v151
	v_cvt_pk_bf16_f32 v172, v152, v153
	v_cvt_pk_bf16_f32 v173, v156, v157
	v_cvt_pk_bf16_f32 v174, v154, v155
	v_cvt_pk_bf16_f32 v175, v158, v159
	v_cvt_pk_bf16_f32 v176, v126, v127
	v_cvt_pk_bf16_f32 v179, v66, v67
	v_cvt_pk_bf16_f32 v182, v64, v65
	v_cvt_pk_bf16_f32 v183, v68, v69
	s_xor_b64 s[0:1], s[0:1], -1
	v_mov_b32_e32 v17, v16
	v_mov_b32_e32 v18, v16
	v_mov_b32_e32 v19, v16
	v_mov_b32_e32 v20, v16
	v_mov_b32_e32 v21, v16
	v_mov_b32_e32 v22, v16
	v_mov_b32_e32 v23, v16
	v_mov_b32_e32 v24, v16
	v_mov_b32_e32 v25, v16
	v_mov_b32_e32 v26, v16
	v_mov_b32_e32 v27, v16
	v_mov_b32_e32 v28, v16
	v_mov_b32_e32 v29, v16
	v_mov_b32_e32 v30, v16
	v_mov_b32_e32 v31, v16
	v_mov_b64_e32 v[44:45], v[12:13]
	v_mov_b64_e32 v[42:43], v[10:11]
	v_mov_b64_e32 v[40:41], v[8:9]
	v_mov_b64_e32 v[38:39], v[6:7]
	v_mov_b64_e32 v[36:37], v[4:5]
	v_mov_b64_e32 v[34:35], v[2:3]
	v_mov_b64_e32 v[32:33], v[0:1]
	v_mov_b64_e32 v[60:61], v[12:13]
	v_mov_b64_e32 v[58:59], v[10:11]
	v_mov_b64_e32 v[56:57], v[8:9]
	v_mov_b64_e32 v[54:55], v[6:7]
	v_mov_b64_e32 v[52:53], v[4:5]
	v_mov_b64_e32 v[50:51], v[2:3]
	v_mov_b64_e32 v[48:49], v[0:1]
	v_mov_b64_e32 v[128:129], v[32:33]
	v_mov_b64_e32 v[130:131], v[34:35]
	v_mov_b64_e32 v[132:133], v[36:37]
	v_mov_b64_e32 v[134:135], v[38:39]
	v_mov_b64_e32 v[136:137], v[40:41]
	v_mov_b64_e32 v[138:139], v[42:43]
	v_mov_b64_e32 v[140:141], v[44:45]
	v_mov_b64_e32 v[142:143], v[46:47]
	v_mov_b64_e32 v[96:97], v[48:49]
	v_mov_b64_e32 v[98:99], v[50:51]
	v_mov_b64_e32 v[100:101], v[52:53]
	v_mov_b64_e32 v[102:103], v[54:55]
	v_mov_b64_e32 v[104:105], v[56:57]
	v_mov_b64_e32 v[106:107], v[58:59]
	v_mov_b64_e32 v[108:109], v[60:61]
	v_mov_b64_e32 v[110:111], v[62:63]
	s_waitcnt lgkmcnt(0)
	s_barrier
	s_branch .LBB0_1198
.LBB0_1196:
	v_add_u32_e32 v0, 0x110, v249
	v_add_u32_e32 v34, 0x12000, v0
	v_add_u32_e32 v42, 0x14000, v0
	ds_read_b64_tr_b16 v[32:33], v34
	ds_read_b64_tr_b16 v[34:35], v34 offset:512
	ds_read_b64_tr_b16 v[40:41], v42
	ds_read_b64_tr_b16 v[42:43], v42 offset:512
	v_cvt_pk_bf16_f32 v36, v112, v113
	v_cvt_pk_bf16_f32 v37, v114, v115
	v_cvt_pk_bf16_f32 v38, v116, v117
	v_cvt_pk_bf16_f32 v39, v118, v119
	v_mov_b32_e32 v252, v14
	v_mov_b32_e32 v253, v15
	s_waitcnt lgkmcnt(2)
	v_mfma_f32_32x32x16_bf16 v[96:111], v[32:35], v[36:39], v[96:111]
	v_add_u32_e32 v34, 0x12400, v0
	ds_read_b64_tr_b16 v[32:33], v34
	ds_read_b64_tr_b16 v[34:35], v34 offset:512
	s_waitcnt lgkmcnt(2)
	v_mfma_f32_32x32x16_bf16 v[128:143], v[40:43], v[36:39], v[128:143]
	v_add_u32_e32 v42, 0x14400, v0
	ds_read_b64_tr_b16 v[40:41], v42
	ds_read_b64_tr_b16 v[42:43], v42 offset:512
	v_cvt_pk_bf16_f32 v36, v120, v121
	v_cvt_pk_bf16_f32 v37, v122, v123
	v_cvt_pk_bf16_f32 v38, v124, v125
	v_cvt_pk_bf16_f32 v39, v126, v127
	s_waitcnt lgkmcnt(2)
	s_nop 0
	v_mfma_f32_32x32x16_bf16 v[96:111], v[32:35], v[36:39], v[96:111]
	v_add_u32_e32 v34, 0x12800, v0
	ds_read_b64_tr_b16 v[32:33], v34
	ds_read_b64_tr_b16 v[34:35], v34 offset:512
	s_waitcnt lgkmcnt(2)
	v_mfma_f32_32x32x16_bf16 v[128:143], v[40:43], v[36:39], v[128:143]
	v_add_u32_e32 v42, 0x14800, v0
	ds_read_b64_tr_b16 v[40:41], v42
	ds_read_b64_tr_b16 v[42:43], v42 offset:512
	v_cvt_pk_bf16_f32 v36, v144, v145
	v_cvt_pk_bf16_f32 v37, v146, v147
	v_cvt_pk_bf16_f32 v38, v148, v149
	v_cvt_pk_bf16_f32 v39, v150, v151
	s_waitcnt lgkmcnt(2)
	s_nop 0
	v_mfma_f32_32x32x16_bf16 v[96:111], v[32:35], v[36:39], v[96:111]
	v_add_u32_e32 v34, 0x12c00, v0
	v_add_u32_e32 v0, 0x14c00, v0
	ds_read_b64_tr_b16 v[32:33], v34
	ds_read_b64_tr_b16 v[34:35], v34 offset:512
	s_waitcnt lgkmcnt(2)
	v_mfma_f32_32x32x16_bf16 v[128:143], v[40:43], v[36:39], v[128:143]
	ds_read_b64_tr_b16 v[40:41], v0
	ds_read_b64_tr_b16 v[42:43], v0 offset:512
	v_cvt_pk_bf16_f32 v36, v152, v153
	v_cvt_pk_bf16_f32 v37, v154, v155
	v_cvt_pk_bf16_f32 v38, v156, v157
	v_cvt_pk_bf16_f32 v39, v158, v159
	s_waitcnt lgkmcnt(2)
	s_nop 0
	v_mfma_f32_32x32x16_bf16 v[96:111], v[32:35], v[36:39], v[96:111]
	s_waitcnt lgkmcnt(0)
	v_mfma_f32_32x32x16_bf16 v[128:143], v[40:43], v[36:39], v[128:143]

; #define MFMA32(a, b, c) __builtin_amdgcn_mfma_f32_32x32x16_bf16((a), (b), (c), 0, 0, 0)
; #define AT_SB __builtin_amdgcn_sched_barrier(0);
; template <int DQK, int MODE, bool QN, bool KN> ...
;     ...
;   auto compute = [&](int it, int bufi) {
;     const int kt = tile_of(it);
;     const int koff = (kt & 1) * 64;
;     const char* sK = smem + bufi * BUF + koff * KROW;
;     const char* sV = smem + bufi * BUF + KBYTES + koff * 64;
;     bool active = (MODE == 0) || (kt * 64 <= qwmax);
;     if (MODE == 2 && active) active = __builtin_amdgcn_ballot_w64(carry >= 1.17549435e-38f) != 0;
;     if (active) {
;       f32x16 sacc[2];
;       const float sinit = fixed_shift ? -sbound : 0.f;
; #pragma unroll
;       for (int kb = 0; kb < 2; ++kb) {
; #pragma unroll
;         for (int i = 0; i < 16; ++i) sacc[kb][i] = sinit;
; #pragma unroll
;         for (int s = 0; s < NS; ++s) {
;           const bf16x8 kf = *(const bf16x8*)(sK + (kb * 32 + r) * KROW + s * 32 + h * 16);
;           sacc[kb] = MFMA32(kf, qf[s], sacc[kb]);
;         }
;       }
;       const bool diag = (MODE != 0) && (kt * 64 + 63 >= q0 + wave * 32);
;       if (MODE != 0 && diag) {
; #pragma unroll
;         for (int kb = 0; kb < 2; ++kb)
; #pragma unroll
;           for (int i = 0; i < 16; ++i) {
;             const int key = kt * 64 + kb * 32 + (i & 3) + 8 * (i >> 2) + 4 * h;
;             if (MODE == 1 ? (key > qrow) : (key >= qrow)) sacc[kb][i] = -INFINITY;
;           }
;       }
;     ...
;     AT_SB AT_GLOAD(rk0, rv0, sg + 2)
.LBB0_1198:
	s_add_i32 s55, s45, -1
	s_min_i32 s2, s55, s13
	s_lshl_b32 s4, s2, 7
	v_add_u32_e32 v0, s4, v238
	v_mad_i64_i32 v[2:3], s[2:3], v0, s36, v[220:221]
	v_add_u32_e32 v0, s4, v239
	v_mad_i64_i32 v[6:7], s[2:3], v0, s36, v[222:223]
	v_add_u32_e32 v0, s4, v240
	v_mad_i64_i32 v[10:11], s[2:3], v0, s36, v[224:225]
	v_add_u32_e32 v0, s4, v241
	v_mad_i64_i32 v[14:15], s[2:3], v0, s37, v[218:219]
	v_add_u32_e32 v0, s4, v242
	global_load_dwordx4 v[2:5], v[2:3], off
	s_nop 0
	global_load_dwordx4 v[6:9], v[6:7], off
	s_nop 0
	global_load_dwordx4 v[10:13], v[10:11], off
	s_nop 0
	global_load_dwordx4 v[204:207], v[14:15], off
	v_mad_i64_i32 v[14:15], s[2:3], v0, s37, v[218:219]
	global_load_dwordx4 v[208:211], v[14:15], off
	s_add_i32 s2, s53, 0xffffff01
	v_cmp_le_i32_e32 vcc, s2, v243
	s_and_saveexec_b64 s[2:3], vcc
	s_cbranch_execz .LBB0_1208
	ds_read_b128 v[64:67], v251
	ds_read_b128 v[68:71], v251 offset:32
	s_add_i32 s4, s53, 0xffffff40
	v_cmp_ge_i32_e32 vcc, s4, v236
	s_waitcnt lgkmcnt(1)
	v_mfma_f32_32x32x16_bf16 v[80:95], v[64:67], v[160:163], v[16:31]
	s_waitcnt lgkmcnt(0)
	v_mfma_f32_32x32x16_bf16 v[80:95], v[68:71], v[164:167], v[80:95]
	ds_read_b128 v[64:67], v251 offset:64
	ds_read_b128 v[68:71], v251 offset:96
	s_waitcnt lgkmcnt(1)
	v_mfma_f32_32x32x16_bf16 v[80:95], v[64:67], v[168:171], v[80:95]
	s_waitcnt lgkmcnt(0)
	v_mfma_f32_32x32x16_bf16 v[80:95], v[68:71], v[172:175], v[80:95]
	ds_read_b128 v[64:67], v251 offset:128
	ds_read_b128 v[68:71], v251 offset:160
	ds_read_b128 v[48:51], v251 offset:6656
	ds_read_b128 v[52:55], v251 offset:6688
	s_waitcnt lgkmcnt(3)
	v_mfma_f32_32x32x16_bf16 v[80:95], v[64:67], v[176:179], v[80:95]
	s_waitcnt lgkmcnt(2)
	v_mfma_f32_32x32x16_bf16 v[80:95], v[68:71], v[180:183], v[80:95]
	s_waitcnt lgkmcnt(1)
	v_mfma_f32_32x32x16_bf16 v[64:79], v[48:51], v[160:163], v[16:31]
	s_waitcnt lgkmcnt(0)
	v_mfma_f32_32x32x16_bf16 v[64:79], v[52:55], v[164:167], v[64:79]
	ds_read_b128 v[48:51], v251 offset:6720
	ds_read_b128 v[52:55], v251 offset:6752
	s_waitcnt lgkmcnt(1)
	v_mfma_f32_32x32x16_bf16 v[64:79], v[48:51], v[168:171], v[64:79]
	s_waitcnt lgkmcnt(0)
	v_mfma_f32_32x32x16_bf16 v[64:79], v[52:55], v[172:175], v[64:79]
	ds_read_b128 v[48:51], v251 offset:6784
	ds_read_b128 v[52:55], v251 offset:6816
	s_waitcnt lgkmcnt(1)
	v_mfma_f32_32x32x16_bf16 v[64:79], v[48:51], v[176:179], v[64:79]
	s_waitcnt lgkmcnt(0)
	v_mfma_f32_32x32x16_bf16 v[64:79], v[52:55], v[180:183], v[64:79]
	s_and_saveexec_b64 s[10:11], vcc
	s_cbranch_execz .LBB0_1201
	v_add_u32_e32 v0, s53, v247
	v_add_u32_e32 v14, 0xffffff01, v0
	v_cmp_lt_i32_e32 vcc, v14, v237
	s_nop 1
	v_cndmask_b32_e32 v81, v234, v81, vcc
	v_cmp_le_i32_e32 vcc, v14, v237
	v_add_u32_e32 v14, 0xffffff03, v0
	s_nop 0
	v_cndmask_b32_e32 v80, v234, v80, vcc
	v_cmp_le_i32_e32 vcc, v14, v237
	v_add_u32_e32 v14, 0xffffff04, v0
	s_nop 0
	v_cndmask_b32_e32 v82, v234, v82, vcc
	v_cmp_le_i32_e32 vcc, v14, v237
	v_add_u32_e32 v14, 0xffffff09, v0
	s_nop 0
	v_cndmask_b32_e32 v83, v234, v83, vcc
	v_cmp_le_i32_e32 vcc, v14, v237
	v_add_u32_e32 v14, 0xffffff0a, v0
	s_nop 0
	v_cndmask_b32_e32 v84, v234, v84, vcc
	v_cmp_le_i32_e32 vcc, v14, v237
	v_add_u32_e32 v14, 0xffffff0b, v0
	s_nop 0
	v_cndmask_b32_e32 v85, v234, v85, vcc
	v_cmp_le_i32_e32 vcc, v14, v237
	v_add_u32_e32 v14, 0xffffff0c, v0
	s_nop 0
	v_cndmask_b32_e32 v86, v234, v86, vcc
	v_cmp_le_i32_e32 vcc, v14, v237
	v_add_u32_e32 v14, 0xffffff11, v0
	s_nop 0
	v_cndmask_b32_e32 v87, v234, v87, vcc
	v_cmp_le_i32_e32 vcc, v14, v237
	v_add_u32_e32 v14, 0xffffff12, v0
	s_nop 0
	v_cndmask_b32_e32 v88, v234, v88, vcc
	v_cmp_le_i32_e32 vcc, v14, v237
	v_add_u32_e32 v14, 0xffffff13, v0
	s_nop 0
	v_cndmask_b32_e32 v89, v234, v89, vcc
	v_cmp_le_i32_e32 vcc, v14, v237
	v_add_u32_e32 v14, 0xffffff14, v0
	s_nop 0
	v_cndmask_b32_e32 v90, v234, v90, vcc
	v_cmp_le_i32_e32 vcc, v14, v237
	v_add_u32_e32 v14, 0xffffff19, v0
	s_nop 0
	v_cndmask_b32_e32 v91, v234, v91, vcc
	v_cmp_le_i32_e32 vcc, v14, v237
	v_add_u32_e32 v14, 0xffffff1a, v0
	s_nop 0
	v_cndmask_b32_e32 v92, v234, v92, vcc
	v_cmp_le_i32_e32 vcc, v14, v237
	v_add_u32_e32 v14, 0xffffff1b, v0
	s_nop 0
	v_cndmask_b32_e32 v93, v234, v93, vcc
	v_cmp_le_i32_e32 vcc, v14, v237
	v_add_u32_e32 v14, 0xffffff1c, v0
	s_nop 0
	v_cndmask_b32_e32 v94, v234, v94, vcc
	v_cmp_le_i32_e32 vcc, v14, v237
	v_add_u32_e32 v14, 0xffffff21, v0
	s_nop 0
	v_cndmask_b32_e32 v95, v234, v95, vcc
	v_cmp_le_i32_e32 vcc, v14, v237
	v_add_u32_e32 v14, 0xffffff22, v0
	s_nop 0
	v_cndmask_b32_e32 v64, v234, v64, vcc
	v_cmp_le_i32_e32 vcc, v14, v237
	v_add_u32_e32 v14, 0xffffff23, v0
	s_nop 0
	v_cndmask_b32_e32 v65, v234, v65, vcc
	v_cmp_le_i32_e32 vcc, v14, v237
	v_add_u32_e32 v14, 0xffffff24, v0
	s_nop 0
	v_cndmask_b32_e32 v66, v234, v66, vcc
	v_cmp_le_i32_e32 vcc, v14, v237
	v_add_u32_e32 v14, 0xffffff29, v0
	s_nop 0
	v_cndmask_b32_e32 v67, v234, v67, vcc
	v_cmp_le_i32_e32 vcc, v14, v237
	v_add_u32_e32 v14, 0xffffff2a, v0
	s_nop 0
	v_cndmask_b32_e32 v68, v234, v68, vcc
	v_cmp_le_i32_e32 vcc, v14, v237
	v_add_u32_e32 v14, 0xffffff2b, v0
	s_nop 0
	v_cndmask_b32_e32 v69, v234, v69, vcc
	v_cmp_le_i32_e32 vcc, v14, v237
	v_add_u32_e32 v14, 0xffffff2c, v0
	s_nop 0
	v_cndmask_b32_e32 v70, v234, v70, vcc
	v_cmp_le_i32_e32 vcc, v14, v237
	v_add_u32_e32 v14, 0xffffff31, v0
	s_nop 0
	v_cndmask_b32_e32 v71, v234, v71, vcc
	v_cmp_le_i32_e32 vcc, v14, v237
	v_add_u32_e32 v14, 0xffffff32, v0
	s_nop 0
	v_cndmask_b32_e32 v72, v234, v72, vcc
	v_cmp_le_i32_e32 vcc, v14, v237
	v_add_u32_e32 v14, 0xffffff33, v0
	s_nop 0
	v_cndmask_b32_e32 v73, v234, v73, vcc
	v_cmp_le_i32_e32 vcc, v14, v237
	v_add_u32_e32 v14, 0xffffff34, v0
	s_nop 0
	v_cndmask_b32_e32 v74, v234, v74, vcc
	v_cmp_le_i32_e32 vcc, v14, v237
	v_add_u32_e32 v14, 0xffffff39, v0
	s_nop 0
	v_cndmask_b32_e32 v75, v234, v75, vcc
	v_cmp_le_i32_e32 vcc, v14, v237
	v_add_u32_e32 v14, 0xffffff3a, v0
	s_nop 0
	v_cndmask_b32_e32 v76, v234, v76, vcc
	v_cmp_le_i32_e32 vcc, v14, v237
	v_add_u32_e32 v14, 0xffffff3b, v0
	v_add_u32_e32 v0, 0xffffff3c, v0
	v_cndmask_b32_e32 v77, v234, v77, vcc
	v_cmp_le_i32_e32 vcc, v14, v237
	s_nop 1
	v_cndmask_b32_e32 v78, v234, v78, vcc
	v_cmp_le_i32_e32 vcc, v0, v237
	s_nop 1
	v_cndmask_b32_e32 v79, v234, v79, vcc
; template <int DQK, int MODE, bool QN, bool KN> ...
;     ...
;         float tmax = -INFINITY;
; #pragma unroll
;         for (int kb = 0; kb < 2; ++kb)
; #pragma unroll
;           for (int i = 0; i < 16; ++i) {
;             tmax = fmaxf(tmax, sacc[kb][i]);
;           }
;         tmax = fmaxf(tmax, __shfl_xor(tmax, 32));
;         const float m_new = fmaxf(m_run, tmax);
;         const float alpha = __builtin_amdgcn_exp2f(m_run - m_new);
;         m_run = m_new;
;         float ps = 0.f;
; #pragma unroll
;         for (int kb = 0; kb < 2; ++kb)
; #pragma unroll
;           for (int i = 0; i < 16; ++i) { const float pv = __builtin_amdgcn_exp2f(sacc[kb][i] - m_new); sacc[kb][i] = pv; ps += pv; }
;         l_run = l_run * alpha + ps;
;         if (__builtin_amdgcn_ballot_w64(alpha != 1.f) != 0) {
; #pragma unroll
;           for (int a = 0; a < 2; ++a)
; #pragma unroll
;             for (int i = 0; i < 16; ++i) o[a][i] *= alpha;
;         }
.LBB0_1201:
	s_or_b64 exec, exec, s[10:11]
	s_andn2_b64 vcc, exec, s[0:1]
	s_mov_b64 s[10:11], -1
	s_cbranch_vccnz .LBB0_1205
	v_max3_f32 v0, v80, s35, v81
	v_max3_f32 v0, v0, v82, v83
	v_max3_f32 v0, v0, v84, v85
	v_max3_f32 v0, v0, v86, v87
	v_max3_f32 v0, v0, v88, v89
	v_max3_f32 v0, v0, v90, v91
	v_max3_f32 v0, v0, v92, v93
	v_max3_f32 v0, v0, v94, v95
	v_max3_f32 v0, v0, v64, v65
	v_max3_f32 v0, v0, v66, v67
	v_max3_f32 v0, v0, v68, v69
	v_max3_f32 v0, v0, v70, v71
	v_max3_f32 v0, v0, v72, v73
	v_max3_f32 v0, v0, v74, v75
	v_max3_f32 v0, v0, v76, v77
	v_max3_f32 v0, v0, v78, v79
	ds_bpermute_b32 v14, v235, v0
	s_waitcnt lgkmcnt(0)
	v_max3_f32 v14, v252, v0, v14
	v_sub_f32_e32 v0, v252, v14
	v_exp_f32_e32 v0, v0
	v_cmp_neq_f32_e32 vcc, 1.0, v0
	s_cbranch_vccz .LBB0_1204
	v_pk_mul_f32 v[110:111], v[110:111], v[0:1] op_sel_hi:[1,0]
	v_pk_mul_f32 v[108:109], v[108:109], v[0:1] op_sel_hi:[1,0]
	v_pk_mul_f32 v[106:107], v[106:107], v[0:1] op_sel_hi:[1,0]
	v_pk_mul_f32 v[104:105], v[104:105], v[0:1] op_sel_hi:[1,0]
	v_pk_mul_f32 v[102:103], v[102:103], v[0:1] op_sel_hi:[1,0]
	v_pk_mul_f32 v[100:101], v[100:101], v[0:1] op_sel_hi:[1,0]
	v_pk_mul_f32 v[98:99], v[98:99], v[0:1] op_sel_hi:[1,0]
	v_pk_mul_f32 v[96:97], v[96:97], v[0:1] op_sel_hi:[1,0]
	v_pk_mul_f32 v[142:143], v[142:143], v[0:1] op_sel_hi:[1,0]
	v_pk_mul_f32 v[140:141], v[140:141], v[0:1] op_sel_hi:[1,0]
	v_pk_mul_f32 v[138:139], v[138:139], v[0:1] op_sel_hi:[1,0]
	v_pk_mul_f32 v[136:137], v[136:137], v[0:1] op_sel_hi:[1,0]
	v_pk_mul_f32 v[134:135], v[134:135], v[0:1] op_sel_hi:[1,0]
	v_pk_mul_f32 v[132:133], v[132:133], v[0:1] op_sel_hi:[1,0]
	v_pk_mul_f32 v[130:131], v[130:131], v[0:1] op_sel_hi:[1,0]
	v_pk_mul_f32 v[128:129], v[128:129], v[0:1] op_sel_hi:[1,0]

; template <int DQK, int MODE, bool QN, bool KN> ...
;     ...
;       } else if (fixed_shift) {
;         float ps = 0.f;
; #pragma unroll
;         for (int kb = 0; kb < 2; ++kb)
; #pragma unroll
;           for (int i = 0; i < 16; ++i) { const float pv = __builtin_amdgcn_exp2f(sacc[kb][i]); sacc[kb][i] = pv; ps += pv; }
;         l_run += ps;
.LBB0_1206:
	v_exp_f32_e32 v112, v80
	v_exp_f32_e32 v113, v81
	v_exp_f32_e32 v114, v82
	v_exp_f32_e32 v115, v83
	v_add_f32_e32 v0, 0, v112
	v_exp_f32_e32 v116, v84
	v_add_f32_e32 v0, v113, v0
	v_exp_f32_e32 v117, v85
	v_add_f32_e32 v0, v114, v0
	v_exp_f32_e32 v118, v86
	v_add_f32_e32 v0, v115, v0
	v_exp_f32_e32 v119, v87
	v_add_f32_e32 v0, v116, v0
	v_exp_f32_e32 v120, v88
	v_add_f32_e32 v0, v117, v0
	v_exp_f32_e32 v121, v89
	v_add_f32_e32 v0, v118, v0
	v_exp_f32_e32 v122, v90
	v_add_f32_e32 v0, v119, v0
	v_exp_f32_e32 v123, v91
	v_add_f32_e32 v0, v120, v0
	v_exp_f32_e32 v124, v92
	v_add_f32_e32 v0, v121, v0
	v_exp_f32_e32 v125, v93
	v_add_f32_e32 v0, v122, v0
	v_exp_f32_e32 v126, v94
	v_add_f32_e32 v0, v123, v0
	v_exp_f32_e32 v127, v95
	v_add_f32_e32 v0, v124, v0
	v_exp_f32_e32 v144, v64
	v_add_f32_e32 v0, v125, v0
	v_exp_f32_e32 v145, v65
	v_add_f32_e32 v0, v126, v0
	v_exp_f32_e32 v146, v66
	v_add_f32_e32 v0, v127, v0
	v_exp_f32_e32 v147, v67
	v_add_f32_e32 v0, v144, v0
	v_exp_f32_e32 v148, v68
	v_add_f32_e32 v0, v145, v0
	v_exp_f32_e32 v149, v69
	v_add_f32_e32 v0, v146, v0
	v_exp_f32_e32 v150, v70
	v_add_f32_e32 v0, v147, v0
	v_exp_f32_e32 v151, v71
	v_add_f32_e32 v0, v148, v0
	v_exp_f32_e32 v152, v72
	v_add_f32_e32 v0, v149, v0
	v_exp_f32_e32 v153, v73
	v_add_f32_e32 v0, v150, v0
	v_exp_f32_e32 v154, v74
	v_add_f32_e32 v0, v151, v0
	v_exp_f32_e32 v155, v75
	v_add_f32_e32 v0, v152, v0
	v_exp_f32_e32 v156, v76
	v_add_f32_e32 v0, v153, v0
	v_exp_f32_e32 v157, v77
	v_add_f32_e32 v0, v154, v0
	v_exp_f32_e32 v158, v78
	v_add_f32_e32 v0, v155, v0
	v_exp_f32_e32 v159, v79
	v_add_f32_e32 v0, v156, v0
	v_add_f32_e32 v0, v157, v0
	v_add_f32_e32 v0, v158, v0
	v_add_f32_e32 v0, v159, v0
	v_add_f32_e32 v15, v253, v0
	v_mov_b32_e32 v14, v252

; #define MFMA32(a, b, c) __builtin_amdgcn_mfma_f32_32x32x16_bf16((a), (b), (c), 0, 0, 0)
; template <int DQK, int MODE, bool QN, bool KN> ...
;     ...
;   auto compute = [&](int it, int bufi) {
;     const int kt = tile_of(it);
;     const int koff = (kt & 1) * 64;
;     const char* sK = smem + bufi * BUF + koff * KROW;
;     const char* sV = smem + bufi * BUF + KBYTES + koff * 64;
;     bool active = (MODE == 0) || (kt * 64 <= qwmax);
;     if (MODE == 2 && active) active = __builtin_amdgcn_ballot_w64(carry >= 1.17549435e-38f) != 0;
;     if (active) {
;       f32x16 sacc[2];
;       const float sinit = fixed_shift ? -sbound : 0.f;
; #pragma unroll
;       for (int kb = 0; kb < 2; ++kb) {
; #pragma unroll
;         for (int i = 0; i < 16; ++i) sacc[kb][i] = sinit;
; #pragma unroll
;         for (int s = 0; s < NS; ++s) {
;           const bf16x8 kf = *(const bf16x8*)(sK + (kb * 32 + r) * KROW + s * 32 + h * 16);
;           sacc[kb] = MFMA32(kf, qf[s], sacc[kb]);
;         }
;       }
;       const bool diag = (MODE != 0) && (kt * 64 + 63 >= q0 + wave * 32);
;       if (MODE != 0 && diag) {
; #pragma unroll
;         for (int kb = 0; kb < 2; ++kb)
; #pragma unroll
;           for (int i = 0; i < 16; ++i) {
;             const int key = kt * 64 + kb * 32 + (i & 3) + 8 * (i >> 2) + 4 * h;
;             if (MODE == 1 ? (key > qrow) : (key >= qrow)) sacc[kb][i] = -INFINITY;
;           }
;       }
.LBB0_1208:
	s_or_b64 exec, exec, s[2:3]
	s_add_i32 s2, s53, 0xffffff41
	v_cmp_le_i32_e32 vcc, s2, v243
	s_and_saveexec_b64 s[2:3], vcc
	s_cbranch_execz .LBB0_1218
	ds_read_b128 v[64:67], v251 offset:13312
	ds_read_b128 v[68:71], v251 offset:13344
	s_add_i32 s4, s53, 0xffffff80
	v_cmp_ge_i32_e32 vcc, s4, v236
	s_waitcnt lgkmcnt(1)
	v_mfma_f32_32x32x16_bf16 v[80:95], v[64:67], v[160:163], v[16:31]
	s_waitcnt lgkmcnt(0)
	v_mfma_f32_32x32x16_bf16 v[80:95], v[68:71], v[164:167], v[80:95]
	ds_read_b128 v[64:67], v251 offset:13376
	ds_read_b128 v[68:71], v251 offset:13408
	s_waitcnt lgkmcnt(1)
	v_mfma_f32_32x32x16_bf16 v[80:95], v[64:67], v[168:171], v[80:95]
	s_waitcnt lgkmcnt(0)
	v_mfma_f32_32x32x16_bf16 v[80:95], v[68:71], v[172:175], v[80:95]
	ds_read_b128 v[64:67], v251 offset:13440
	ds_read_b128 v[68:71], v251 offset:13472
	ds_read_b128 v[48:51], v251 offset:19968
	ds_read_b128 v[52:55], v251 offset:20000
	s_waitcnt lgkmcnt(3)
	v_mfma_f32_32x32x16_bf16 v[80:95], v[64:67], v[176:179], v[80:95]
	s_waitcnt lgkmcnt(2)
	v_mfma_f32_32x32x16_bf16 v[80:95], v[68:71], v[180:183], v[80:95]
	s_waitcnt lgkmcnt(1)
	v_mfma_f32_32x32x16_bf16 v[64:79], v[48:51], v[160:163], v[16:31]
	s_waitcnt lgkmcnt(0)
	v_mfma_f32_32x32x16_bf16 v[64:79], v[52:55], v[164:167], v[64:79]
	ds_read_b128 v[48:51], v251 offset:20032
	ds_read_b128 v[52:55], v251 offset:20064
	s_waitcnt lgkmcnt(1)
	v_mfma_f32_32x32x16_bf16 v[64:79], v[48:51], v[168:171], v[64:79]
	s_waitcnt lgkmcnt(0)
	v_mfma_f32_32x32x16_bf16 v[64:79], v[52:55], v[172:175], v[64:79]
	ds_read_b128 v[48:51], v251 offset:20096
	ds_read_b128 v[52:55], v251 offset:20128
	s_waitcnt lgkmcnt(1)
	v_mfma_f32_32x32x16_bf16 v[64:79], v[48:51], v[176:179], v[64:79]
	s_waitcnt lgkmcnt(0)
	v_mfma_f32_32x32x16_bf16 v[64:79], v[52:55], v[180:183], v[64:79]
	s_and_saveexec_b64 s[10:11], vcc
	s_cbranch_execz .LBB0_1211
	v_add_u32_e32 v0, s53, v247
	v_add_u32_e32 v14, 0xffffff41, v0
	v_cmp_le_i32_e32 vcc, v14, v237
	v_add_u32_e32 v14, 0xffffff42, v0
	s_nop 0
	v_cndmask_b32_e32 v80, v234, v80, vcc
	v_cmp_le_i32_e32 vcc, v14, v237
	v_add_u32_e32 v14, 0xffffff43, v0
	s_nop 0
	v_cndmask_b32_e32 v81, v234, v81, vcc
	v_cmp_le_i32_e32 vcc, v14, v237
	v_add_u32_e32 v14, 0xffffff44, v0
	s_nop 0
	v_cndmask_b32_e32 v82, v234, v82, vcc
	v_cmp_le_i32_e32 vcc, v14, v237
	v_add_u32_e32 v14, 0xffffff49, v0
	s_nop 0
	v_cndmask_b32_e32 v83, v234, v83, vcc
	v_cmp_le_i32_e32 vcc, v14, v237
	v_add_u32_e32 v14, 0xffffff4a, v0
	s_nop 0
	v_cndmask_b32_e32 v84, v234, v84, vcc
	v_cmp_le_i32_e32 vcc, v14, v237
	v_add_u32_e32 v14, 0xffffff4b, v0
	s_nop 0
	v_cndmask_b32_e32 v85, v234, v85, vcc
	v_cmp_le_i32_e32 vcc, v14, v237
	v_add_u32_e32 v14, 0xffffff4c, v0
	s_nop 0
	v_cndmask_b32_e32 v86, v234, v86, vcc
	v_cmp_le_i32_e32 vcc, v14, v237
	v_add_u32_e32 v14, 0xffffff51, v0
	s_nop 0
	v_cndmask_b32_e32 v87, v234, v87, vcc
	v_cmp_le_i32_e32 vcc, v14, v237
	v_add_u32_e32 v14, 0xffffff52, v0
	s_nop 0
	v_cndmask_b32_e32 v88, v234, v88, vcc
	v_cmp_le_i32_e32 vcc, v14, v237
	v_add_u32_e32 v14, 0xffffff53, v0
	s_nop 0
	v_cndmask_b32_e32 v89, v234, v89, vcc
	v_cmp_le_i32_e32 vcc, v14, v237
	v_add_u32_e32 v14, 0xffffff54, v0
	s_nop 0
	v_cndmask_b32_e32 v90, v234, v90, vcc
	v_cmp_le_i32_e32 vcc, v14, v237
	v_add_u32_e32 v14, 0xffffff59, v0
	s_nop 0
	v_cndmask_b32_e32 v91, v234, v91, vcc
	v_cmp_le_i32_e32 vcc, v14, v237
	v_add_u32_e32 v14, 0xffffff5a, v0
	s_nop 0
	v_cndmask_b32_e32 v92, v234, v92, vcc
	v_cmp_le_i32_e32 vcc, v14, v237
	v_add_u32_e32 v14, 0xffffff5b, v0
	s_nop 0
	v_cndmask_b32_e32 v93, v234, v93, vcc
	v_cmp_le_i32_e32 vcc, v14, v237
	v_add_u32_e32 v14, 0xffffff5c, v0
	s_nop 0
	v_cndmask_b32_e32 v94, v234, v94, vcc
	v_cmp_le_i32_e32 vcc, v14, v237
	v_add_u32_e32 v14, 0xffffff61, v0
	s_nop 0
	v_cndmask_b32_e32 v95, v234, v95, vcc
	v_cmp_le_i32_e32 vcc, v14, v237
	v_add_u32_e32 v14, 0xffffff62, v0
	s_nop 0
	v_cndmask_b32_e32 v64, v234, v64, vcc
	v_cmp_le_i32_e32 vcc, v14, v237
	v_add_u32_e32 v14, 0xffffff63, v0
	s_nop 0
	v_cndmask_b32_e32 v65, v234, v65, vcc
	v_cmp_le_i32_e32 vcc, v14, v237
	v_add_u32_e32 v14, 0xffffff64, v0
	s_nop 0
	v_cndmask_b32_e32 v66, v234, v66, vcc
	v_cmp_le_i32_e32 vcc, v14, v237
	v_add_u32_e32 v14, 0xffffff69, v0
	s_nop 0
	v_cndmask_b32_e32 v67, v234, v67, vcc
	v_cmp_le_i32_e32 vcc, v14, v237
	v_add_u32_e32 v14, 0xffffff6a, v0
	s_nop 0
	v_cndmask_b32_e32 v68, v234, v68, vcc
	v_cmp_le_i32_e32 vcc, v14, v237
	v_add_u32_e32 v14, 0xffffff6b, v0
	s_nop 0
	v_cndmask_b32_e32 v69, v234, v69, vcc
	v_cmp_le_i32_e32 vcc, v14, v237
	v_add_u32_e32 v14, 0xffffff6c, v0
	s_nop 0
	v_cndmask_b32_e32 v70, v234, v70, vcc
	v_cmp_le_i32_e32 vcc, v14, v237
	v_add_u32_e32 v14, 0xffffff71, v0
	s_nop 0
	v_cndmask_b32_e32 v71, v234, v71, vcc
	v_cmp_le_i32_e32 vcc, v14, v237
	v_add_u32_e32 v14, 0xffffff72, v0
	s_nop 0
	v_cndmask_b32_e32 v72, v234, v72, vcc
	v_cmp_le_i32_e32 vcc, v14, v237
	v_add_u32_e32 v14, 0xffffff73, v0
	s_nop 0
	v_cndmask_b32_e32 v73, v234, v73, vcc
	v_cmp_le_i32_e32 vcc, v14, v237
	v_add_u32_e32 v14, 0xffffff74, v0
	s_nop 0
	v_cndmask_b32_e32 v74, v234, v74, vcc
	v_cmp_le_i32_e32 vcc, v14, v237
	v_add_u32_e32 v14, 0xffffff79, v0
	s_nop 0
	v_cndmask_b32_e32 v75, v234, v75, vcc
	v_cmp_le_i32_e32 vcc, v14, v237
	v_add_u32_e32 v14, 0xffffff7a, v0
	s_nop 0
	v_cndmask_b32_e32 v76, v234, v76, vcc
	v_cmp_le_i32_e32 vcc, v14, v237
	v_add_u32_e32 v14, 0xffffff7b, v0
	v_add_u32_e32 v0, 0xffffff7c, v0
	v_cndmask_b32_e32 v77, v234, v77, vcc
	v_cmp_le_i32_e32 vcc, v14, v237
	s_nop 1
	v_cndmask_b32_e32 v78, v234, v78, vcc
	v_cmp_le_i32_e32 vcc, v0, v237
	s_nop 1
	v_cndmask_b32_e32 v79, v234, v79, vcc

; #define MFMA32(a, b, c) __builtin_amdgcn_mfma_f32_32x32x16_bf16((a), (b), (c), 0, 0, 0)
; #define AT_SB __builtin_amdgcn_sched_barrier(0);
; template <int DQK, int MODE, bool QN, bool KN> ...
;     ...
;   auto compute = [&](int it, int bufi) {
;     const int kt = tile_of(it);
;     const int koff = (kt & 1) * 64;
;     const char* sK = smem + bufi * BUF + koff * KROW;
;     const char* sV = smem + bufi * BUF + KBYTES + koff * 64;
;     bool active = (MODE == 0) || (kt * 64 <= qwmax);
;     if (MODE == 2 && active) active = __builtin_amdgcn_ballot_w64(carry >= 1.17549435e-38f) != 0;
;     if (active) {
;       f32x16 sacc[2];
;       const float sinit = fixed_shift ? -sbound : 0.f;
; #pragma unroll
;       for (int kb = 0; kb < 2; ++kb) {
; #pragma unroll
;         for (int i = 0; i < 16; ++i) sacc[kb][i] = sinit;
; #pragma unroll
;         for (int s = 0; s < NS; ++s) {
;           const bf16x8 kf = *(const bf16x8*)(sK + (kb * 32 + r) * KROW + s * 32 + h * 16);
;           sacc[kb] = MFMA32(kf, qf[s], sacc[kb]);
;         }
;       }
;       const bool diag = (MODE != 0) && (kt * 64 + 63 >= q0 + wave * 32);
;       if (MODE != 0 && diag) {
; #pragma unroll
;         for (int kb = 0; kb < 2; ++kb)
; #pragma unroll
;           for (int i = 0; i < 16; ++i) {
;             const int key = kt * 64 + kb * 32 + (i & 3) + 8 * (i >> 2) + 4 * h;
;             if (MODE == 1 ? (key > qrow) : (key >= qrow)) sacc[kb][i] = -INFINITY;
;           }
;       }
;     ...
;     AT_SB AT_GLOAD(rk0, rv0, sg + 2)
;     AT_SB compute(2 * sg, 0); compute(2 * sg + 1, 0); AT_SB
;     AT_SWRITE(rk1, rv1, 1)
;     if (MODE == 2) { if (__syncthreads_and(carry < 1.17549435e-38f)) break; } else { __syncthreads(); }
;     AT_SB AT_GLOAD(rk1, rv1, sg + 3)
;     AT_SB compute(2 * sg + 2, 1); compute(2 * sg + 3, 1); AT_SB
;     AT_SWRITE(rk0, rv0, 0)
;     if (MODE == 2) { if (__syncthreads_and(carry < 1.17549435e-38f)) break; } else { __syncthreads(); }
.LBB0_1218:
	s_or_b64 exec, exec, s[2:3]
	s_waitcnt vmcnt(9)
	ds_write_b128 v244, v[184:187] offset:43008
	s_waitcnt vmcnt(8)
	ds_write_b128 v245, v[188:191] offset:43008
	s_waitcnt vmcnt(7)
	ds_write_b128 v246, v[192:195] offset:43008
	s_waitcnt vmcnt(6)
	ds_write_b128 v250, v[196:199]
	s_waitcnt vmcnt(5)
	ds_write_b128 v250, v[200:203] offset:4096
	s_waitcnt lgkmcnt(0)
	s_barrier
	s_min_i32 s2, s45, s13
	s_lshl_b32 s4, s2, 7
	v_add_u32_e32 v0, s4, v238
	v_mad_i64_i32 v[14:15], s[2:3], v0, s36, v[220:221]
	v_add_u32_e32 v0, s4, v239
	v_mad_i64_i32 v[64:65], s[2:3], v0, s36, v[222:223]
	v_add_u32_e32 v0, s4, v240
	global_load_dwordx4 v[184:187], v[14:15], off
	global_load_dwordx4 v[188:191], v[64:65], off
	v_mad_i64_i32 v[14:15], s[2:3], v0, s36, v[224:225]
	v_add_u32_e32 v0, s4, v241
	v_mad_i64_i32 v[64:65], s[2:3], v0, s37, v[218:219]
	v_add_u32_e32 v0, s4, v242
	global_load_dwordx4 v[192:195], v[14:15], off
	global_load_dwordx4 v[196:199], v[64:65], off
	v_mad_i64_i32 v[14:15], s[2:3], v0, s37, v[218:219]
	global_load_dwordx4 v[200:203], v[14:15], off
	s_add_i32 s2, s53, 0xffffff81
	v_cmp_le_i32_e32 vcc, s2, v243
	s_and_saveexec_b64 s[2:3], vcc
	s_cbranch_execz .LBB0_1228
	ds_read_b128 v[64:67], v251 offset:43008
	ds_read_b128 v[68:71], v251 offset:43040
	s_sub_i32 s4, s53, 64
	v_cmp_ge_i32_e32 vcc, s4, v236
	s_waitcnt lgkmcnt(1)
	v_mfma_f32_32x32x16_bf16 v[80:95], v[64:67], v[160:163], v[16:31]
	s_waitcnt lgkmcnt(0)
	v_mfma_f32_32x32x16_bf16 v[80:95], v[68:71], v[164:167], v[80:95]
	ds_read_b128 v[64:67], v251 offset:43072
	ds_read_b128 v[68:71], v251 offset:43104
	s_waitcnt lgkmcnt(1)
	v_mfma_f32_32x32x16_bf16 v[80:95], v[64:67], v[168:171], v[80:95]
	s_waitcnt lgkmcnt(0)
	v_mfma_f32_32x32x16_bf16 v[80:95], v[68:71], v[172:175], v[80:95]
	ds_read_b128 v[64:67], v251 offset:43136
	ds_read_b128 v[68:71], v251 offset:43168
	ds_read_b128 v[48:51], v251 offset:49664
	ds_read_b128 v[52:55], v251 offset:49696
	s_waitcnt lgkmcnt(3)
	v_mfma_f32_32x32x16_bf16 v[80:95], v[64:67], v[176:179], v[80:95]
	s_waitcnt lgkmcnt(2)
	v_mfma_f32_32x32x16_bf16 v[80:95], v[68:71], v[180:183], v[80:95]
	s_waitcnt lgkmcnt(1)
	v_mfma_f32_32x32x16_bf16 v[64:79], v[48:51], v[160:163], v[16:31]
	s_waitcnt lgkmcnt(0)
	v_mfma_f32_32x32x16_bf16 v[64:79], v[52:55], v[164:167], v[64:79]
	ds_read_b128 v[48:51], v251 offset:49728
	ds_read_b128 v[52:55], v251 offset:49760
	s_waitcnt lgkmcnt(1)
	v_mfma_f32_32x32x16_bf16 v[64:79], v[48:51], v[168:171], v[64:79]
	s_waitcnt lgkmcnt(0)
	v_mfma_f32_32x32x16_bf16 v[64:79], v[52:55], v[172:175], v[64:79]
	ds_read_b128 v[48:51], v251 offset:49792
	ds_read_b128 v[52:55], v251 offset:49824
	s_waitcnt lgkmcnt(1)
	v_mfma_f32_32x32x16_bf16 v[64:79], v[48:51], v[176:179], v[64:79]
	s_waitcnt lgkmcnt(0)
	v_mfma_f32_32x32x16_bf16 v[64:79], v[52:55], v[180:183], v[64:79]
	s_and_saveexec_b64 s[10:11], vcc
	s_cbranch_execz .LBB0_1221
	v_add_u32_e32 v0, s53, v247
	v_add_u32_e32 v14, 0xffffff81, v0
	v_cmp_le_i32_e32 vcc, v14, v237
	v_add_u32_e32 v14, 0xffffff82, v0
	s_nop 0
	v_cndmask_b32_e32 v80, v234, v80, vcc
	v_cmp_le_i32_e32 vcc, v14, v237
	v_add_u32_e32 v14, 0xffffff83, v0
	s_nop 0
	v_cndmask_b32_e32 v81, v234, v81, vcc
	v_cmp_le_i32_e32 vcc, v14, v237
	v_add_u32_e32 v14, 0xffffff84, v0
	s_nop 0
	v_cndmask_b32_e32 v82, v234, v82, vcc
	v_cmp_le_i32_e32 vcc, v14, v237
	v_add_u32_e32 v14, 0xffffff89, v0
	s_nop 0
	v_cndmask_b32_e32 v83, v234, v83, vcc
	v_cmp_le_i32_e32 vcc, v14, v237
	v_add_u32_e32 v14, 0xffffff8a, v0
	s_nop 0
	v_cndmask_b32_e32 v84, v234, v84, vcc
	v_cmp_le_i32_e32 vcc, v14, v237
	v_add_u32_e32 v14, 0xffffff8b, v0
	s_nop 0
	v_cndmask_b32_e32 v85, v234, v85, vcc
	v_cmp_le_i32_e32 vcc, v14, v237
	v_add_u32_e32 v14, 0xffffff8c, v0
	s_nop 0
	v_cndmask_b32_e32 v86, v234, v86, vcc
	v_cmp_le_i32_e32 vcc, v14, v237
	v_add_u32_e32 v14, 0xffffff91, v0
	s_nop 0
	v_cndmask_b32_e32 v87, v234, v87, vcc
	v_cmp_le_i32_e32 vcc, v14, v237
	v_add_u32_e32 v14, 0xffffff92, v0
	s_nop 0
	v_cndmask_b32_e32 v88, v234, v88, vcc
	v_cmp_le_i32_e32 vcc, v14, v237
	v_add_u32_e32 v14, 0xffffff93, v0
	s_nop 0
	v_cndmask_b32_e32 v89, v234, v89, vcc
	v_cmp_le_i32_e32 vcc, v14, v237
	v_add_u32_e32 v14, 0xffffff94, v0
	s_nop 0
	v_cndmask_b32_e32 v90, v234, v90, vcc
	v_cmp_le_i32_e32 vcc, v14, v237
	v_add_u32_e32 v14, 0xffffff99, v0
	s_nop 0
	v_cndmask_b32_e32 v91, v234, v91, vcc
	v_cmp_le_i32_e32 vcc, v14, v237
	v_add_u32_e32 v14, 0xffffff9a, v0
	s_nop 0
	v_cndmask_b32_e32 v92, v234, v92, vcc
	v_cmp_le_i32_e32 vcc, v14, v237
	v_add_u32_e32 v14, 0xffffff9b, v0
	s_nop 0
	v_cndmask_b32_e32 v93, v234, v93, vcc
	v_cmp_le_i32_e32 vcc, v14, v237
	v_add_u32_e32 v14, 0xffffff9c, v0
	s_nop 0
	v_cndmask_b32_e32 v94, v234, v94, vcc
	v_cmp_le_i32_e32 vcc, v14, v237
	v_add_u32_e32 v14, 0xffffffa1, v0
	s_nop 0
	v_cndmask_b32_e32 v95, v234, v95, vcc
	v_cmp_le_i32_e32 vcc, v14, v237
	v_add_u32_e32 v14, 0xffffffa2, v0
	s_nop 0
	v_cndmask_b32_e32 v64, v234, v64, vcc
	v_cmp_le_i32_e32 vcc, v14, v237
	v_add_u32_e32 v14, 0xffffffa3, v0
	s_nop 0
	v_cndmask_b32_e32 v65, v234, v65, vcc
	v_cmp_le_i32_e32 vcc, v14, v237
	v_add_u32_e32 v14, 0xffffffa4, v0
	s_nop 0
	v_cndmask_b32_e32 v66, v234, v66, vcc
	v_cmp_le_i32_e32 vcc, v14, v237
	v_add_u32_e32 v14, 0xffffffa9, v0
	s_nop 0
	v_cndmask_b32_e32 v67, v234, v67, vcc
	v_cmp_le_i32_e32 vcc, v14, v237
	v_add_u32_e32 v14, 0xffffffaa, v0
	s_nop 0
	v_cndmask_b32_e32 v68, v234, v68, vcc
	v_cmp_le_i32_e32 vcc, v14, v237
	v_add_u32_e32 v14, 0xffffffab, v0
	s_nop 0
	v_cndmask_b32_e32 v69, v234, v69, vcc
	v_cmp_le_i32_e32 vcc, v14, v237
	v_add_u32_e32 v14, 0xffffffac, v0
	s_nop 0
	v_cndmask_b32_e32 v70, v234, v70, vcc
	v_cmp_le_i32_e32 vcc, v14, v237
	v_add_u32_e32 v14, 0xffffffb1, v0
	s_nop 0
	v_cndmask_b32_e32 v71, v234, v71, vcc
	v_cmp_le_i32_e32 vcc, v14, v237
	v_add_u32_e32 v14, 0xffffffb2, v0
	s_nop 0
	v_cndmask_b32_e32 v72, v234, v72, vcc
	v_cmp_le_i32_e32 vcc, v14, v237
	v_add_u32_e32 v14, 0xffffffb3, v0
	s_nop 0
	v_cndmask_b32_e32 v73, v234, v73, vcc
	v_cmp_le_i32_e32 vcc, v14, v237
	v_add_u32_e32 v14, 0xffffffb4, v0
	s_nop 0
	v_cndmask_b32_e32 v74, v234, v74, vcc
	v_cmp_le_i32_e32 vcc, v14, v237
	v_add_u32_e32 v14, 0xffffffb9, v0
	s_nop 0
	v_cndmask_b32_e32 v75, v234, v75, vcc
	v_cmp_le_i32_e32 vcc, v14, v237
	v_add_u32_e32 v14, 0xffffffba, v0
	s_nop 0
	v_cndmask_b32_e32 v76, v234, v76, vcc
	v_cmp_le_i32_e32 vcc, v14, v237
	v_add_u32_e32 v14, 0xffffffbb, v0
	v_add_u32_e32 v0, 0xffffffbc, v0
	v_cndmask_b32_e32 v77, v234, v77, vcc
	v_cmp_le_i32_e32 vcc, v14, v237
	s_nop 1
	v_cndmask_b32_e32 v78, v234, v78, vcc
	v_cmp_le_i32_e32 vcc, v0, v237
	s_nop 1
	v_cndmask_b32_e32 v79, v234, v79, vcc

; DI unsigned pack2(float a, float b) { bf2_t v = __builtin_convertvector((f32x2){a, b}, bf2_t); return __builtin_bit_cast(unsigned, v); }
; #define MFMA32(a, b, c) __builtin_amdgcn_mfma_f32_32x32x16_bf16((a), (b), (c), 0, 0, 0)
; template <int DQK, int MODE, bool QN, bool KN> ...
;     ...
; #pragma unroll
;       for (int kb = 0; kb < 2; ++kb)
; #pragma unroll
;         for (int s2 = 0; s2 < 2; ++s2) {
;           u32x4 pw;
;           pw.x = pack2(sacc[kb][8 * s2 + 0], sacc[kb][8 * s2 + 1]); pw.y = pack2(sacc[kb][8 * s2 + 2], sacc[kb][8 * s2 + 3]);
;           pw.z = pack2(sacc[kb][8 * s2 + 4], sacc[kb][8 * s2 + 5]); pw.w = pack2(sacc[kb][8 * s2 + 6], sacc[kb][8 * s2 + 7]);
;           const bf16x8 pf = __builtin_bit_cast(bf16x8, pw);
; #pragma unroll
;           for (int dvb = 0; dvb < 2; ++dvb) {
;             const char* vb = sV + dvb * VIMG + (kb * 32 + 16 * s2) * 64 + vtr_off;
;             const s16x4 v0 = tr_read(vb), v1 = tr_read(vb + 8 * 64);
;             const bf16x8 vf = __builtin_shufflevector(v0, v1, 0, 1, 2, 3, 4, 5, 6, 7);
;             o[dvb] = MFMA32(vf, pf, o[dvb]);
;           }
;         }
.LBB0_1227:
	v_add_u32_e32 v0, 0x110, v249
	v_add_u32_e32 v34, 0x11000, v0
	v_add_u32_e32 v42, 0x13000, v0
	ds_read_b64_tr_b16 v[32:33], v34
	ds_read_b64_tr_b16 v[34:35], v34 offset:512
	ds_read_b64_tr_b16 v[40:41], v42
	ds_read_b64_tr_b16 v[42:43], v42 offset:512
	v_cvt_pk_bf16_f32 v36, v112, v113
	v_cvt_pk_bf16_f32 v37, v114, v115
	v_cvt_pk_bf16_f32 v38, v116, v117
	v_cvt_pk_bf16_f32 v39, v118, v119
	v_mov_b32_e32 v252, v14
	v_mov_b32_e32 v253, v15
	s_waitcnt lgkmcnt(2)
	v_mfma_f32_32x32x16_bf16 v[96:111], v[32:35], v[36:39], v[96:111]
	v_add_u32_e32 v34, 0x11400, v0
	ds_read_b64_tr_b16 v[32:33], v34
	ds_read_b64_tr_b16 v[34:35], v34 offset:512
	s_waitcnt lgkmcnt(2)
	v_mfma_f32_32x32x16_bf16 v[128:143], v[40:43], v[36:39], v[128:143]
	v_add_u32_e32 v42, 0x13400, v0
	ds_read_b64_tr_b16 v[40:41], v42
	ds_read_b64_tr_b16 v[42:43], v42 offset:512
	v_cvt_pk_bf16_f32 v36, v120, v121
	v_cvt_pk_bf16_f32 v37, v122, v123
	v_cvt_pk_bf16_f32 v38, v124, v125
	v_cvt_pk_bf16_f32 v39, v126, v127
	s_waitcnt lgkmcnt(2)
	s_nop 0
	v_mfma_f32_32x32x16_bf16 v[96:111], v[32:35], v[36:39], v[96:111]
	v_add_u32_e32 v34, 0x11800, v0
	ds_read_b64_tr_b16 v[32:33], v34
	ds_read_b64_tr_b16 v[34:35], v34 offset:512
	s_waitcnt lgkmcnt(2)
	v_mfma_f32_32x32x16_bf16 v[128:143], v[40:43], v[36:39], v[128:143]
	v_add_u32_e32 v42, 0x13800, v0
	ds_read_b64_tr_b16 v[40:41], v42
	ds_read_b64_tr_b16 v[42:43], v42 offset:512
	v_cvt_pk_bf16_f32 v36, v144, v145
	v_cvt_pk_bf16_f32 v37, v146, v147
	v_cvt_pk_bf16_f32 v38, v148, v149
	v_cvt_pk_bf16_f32 v39, v150, v151
	s_waitcnt lgkmcnt(2)
	s_nop 0
	v_mfma_f32_32x32x16_bf16 v[96:111], v[32:35], v[36:39], v[96:111]
	v_add_u32_e32 v34, 0x11c00, v0
	v_add_u32_e32 v0, 0x13c00, v0
	ds_read_b64_tr_b16 v[32:33], v34
	ds_read_b64_tr_b16 v[34:35], v34 offset:512
	s_waitcnt lgkmcnt(2)
	v_mfma_f32_32x32x16_bf16 v[128:143], v[40:43], v[36:39], v[128:143]
	ds_read_b64_tr_b16 v[40:41], v0
	ds_read_b64_tr_b16 v[42:43], v0 offset:512
	v_cvt_pk_bf16_f32 v36, v152, v153
	v_cvt_pk_bf16_f32 v37, v154, v155
	v_cvt_pk_bf16_f32 v38, v156, v157
	v_cvt_pk_bf16_f32 v39, v158, v159
	s_waitcnt lgkmcnt(2)
	s_nop 0
	v_mfma_f32_32x32x16_bf16 v[96:111], v[32:35], v[36:39], v[96:111]
	s_waitcnt lgkmcnt(0)
	v_mfma_f32_32x32x16_bf16 v[128:143], v[40:43], v[36:39], v[128:143]
; #define MFMA32(a, b, c) __builtin_amdgcn_mfma_f32_32x32x16_bf16((a), (b), (c), 0, 0, 0)
; template <int DQK, int MODE, bool QN, bool KN> ...
;     ...
;   auto compute = [&](int it, int bufi) {
;     const int kt = tile_of(it);
;     const int koff = (kt & 1) * 64;
;     const char* sK = smem + bufi * BUF + koff * KROW;
;     const char* sV = smem + bufi * BUF + KBYTES + koff * 64;
;     bool active = (MODE == 0) || (kt * 64 <= qwmax);
;     if (MODE == 2 && active) active = __builtin_amdgcn_ballot_w64(carry >= 1.17549435e-38f) != 0;
;     if (active) {
;       f32x16 sacc[2];
;       const float sinit = fixed_shift ? -sbound : 0.f;
; #pragma unroll
;       for (int kb = 0; kb < 2; ++kb) {
; #pragma unroll
;         for (int i = 0; i < 16; ++i) sacc[kb][i] = sinit;
; #pragma unroll
;         for (int s = 0; s < NS; ++s) {
;           const bf16x8 kf = *(const bf16x8*)(sK + (kb * 32 + r) * KROW + s * 32 + h * 16);
;           sacc[kb] = MFMA32(kf, qf[s], sacc[kb]);
;         }
;       }
;       const bool diag = (MODE != 0) && (kt * 64 + 63 >= q0 + wave * 32);
;       if (MODE != 0 && diag) {
; #pragma unroll
;         for (int kb = 0; kb < 2; ++kb)
; #pragma unroll
;           for (int i = 0; i < 16; ++i) {
;             const int key = kt * 64 + kb * 32 + (i & 3) + 8 * (i >> 2) + 4 * h;
;             if (MODE == 1 ? (key > qrow) : (key >= qrow)) sacc[kb][i] = -INFINITY;
;           }
;       }
.LBB0_1228:
	s_or_b64 exec, exec, s[2:3]
	s_sub_i32 s2, s53, 63
	v_cmp_le_i32_e32 vcc, s2, v243
	s_and_saveexec_b64 s[2:3], vcc
	s_cbranch_execz .LBB0_1197
	ds_read_b128 v[64:67], v251 offset:56320
	ds_read_b128 v[68:71], v251 offset:56352
	v_cmp_ge_i32_e32 vcc, s53, v236
	s_waitcnt lgkmcnt(1)
	v_mfma_f32_32x32x16_bf16 v[80:95], v[64:67], v[160:163], v[16:31]
	s_waitcnt lgkmcnt(0)
	v_mfma_f32_32x32x16_bf16 v[80:95], v[68:71], v[164:167], v[80:95]
	ds_read_b128 v[64:67], v251 offset:56384
	ds_read_b128 v[68:71], v251 offset:56416
	s_waitcnt lgkmcnt(1)
	v_mfma_f32_32x32x16_bf16 v[80:95], v[64:67], v[168:171], v[80:95]
	s_waitcnt lgkmcnt(0)
	v_mfma_f32_32x32x16_bf16 v[80:95], v[68:71], v[172:175], v[80:95]
	ds_read_b128 v[64:67], v251 offset:56448
	ds_read_b128 v[68:71], v251 offset:56480
	ds_read_b128 v[48:51], v251 offset:62976
	ds_read_b128 v[52:55], v251 offset:63008
	s_waitcnt lgkmcnt(3)
	v_mfma_f32_32x32x16_bf16 v[80:95], v[64:67], v[176:179], v[80:95]
	s_waitcnt lgkmcnt(2)
	v_mfma_f32_32x32x16_bf16 v[80:95], v[68:71], v[180:183], v[80:95]
	s_waitcnt lgkmcnt(1)
	v_mfma_f32_32x32x16_bf16 v[64:79], v[48:51], v[160:163], v[16:31]
	s_waitcnt lgkmcnt(0)
	v_mfma_f32_32x32x16_bf16 v[64:79], v[52:55], v[164:167], v[64:79]
	ds_read_b128 v[48:51], v251 offset:63040
	ds_read_b128 v[52:55], v251 offset:63072
	s_waitcnt lgkmcnt(1)
	v_mfma_f32_32x32x16_bf16 v[64:79], v[48:51], v[168:171], v[64:79]
	s_waitcnt lgkmcnt(0)
	v_mfma_f32_32x32x16_bf16 v[64:79], v[52:55], v[172:175], v[64:79]
	ds_read_b128 v[48:51], v251 offset:63104
	ds_read_b128 v[52:55], v251 offset:63136
	s_waitcnt lgkmcnt(1)
	v_mfma_f32_32x32x16_bf16 v[64:79], v[48:51], v[176:179], v[64:79]
	s_waitcnt lgkmcnt(0)
	v_mfma_f32_32x32x16_bf16 v[64:79], v[52:55], v[180:183], v[64:79]
	s_and_saveexec_b64 s[10:11], vcc
	s_cbranch_execz .LBB0_1231
	v_add_u32_e32 v0, s53, v247
	v_subrev_u32_e32 v14, 63, v0
	v_cmp_le_i32_e32 vcc, v14, v237
	v_subrev_u32_e32 v14, 62, v0
	s_nop 0
	v_cndmask_b32_e32 v80, v234, v80, vcc
	v_cmp_le_i32_e32 vcc, v14, v237
	v_subrev_u32_e32 v14, 61, v0
	s_nop 0
	v_cndmask_b32_e32 v81, v234, v81, vcc
	v_cmp_le_i32_e32 vcc, v14, v237
	v_subrev_u32_e32 v14, 60, v0
	s_nop 0
	v_cndmask_b32_e32 v82, v234, v82, vcc
	v_cmp_le_i32_e32 vcc, v14, v237
	v_subrev_u32_e32 v14, 55, v0
	s_nop 0
	v_cndmask_b32_e32 v83, v234, v83, vcc
	v_cmp_le_i32_e32 vcc, v14, v237
	v_subrev_u32_e32 v14, 54, v0
	s_nop 0
	v_cndmask_b32_e32 v84, v234, v84, vcc
	v_cmp_le_i32_e32 vcc, v14, v237
	v_subrev_u32_e32 v14, 53, v0
	s_nop 0
	v_cndmask_b32_e32 v85, v234, v85, vcc
	v_cmp_le_i32_e32 vcc, v14, v237
	v_subrev_u32_e32 v14, 52, v0
	s_nop 0
	v_cndmask_b32_e32 v86, v234, v86, vcc
	v_cmp_le_i32_e32 vcc, v14, v237
	v_subrev_u32_e32 v14, 47, v0
	s_nop 0
	v_cndmask_b32_e32 v87, v234, v87, vcc
	v_cmp_le_i32_e32 vcc, v14, v237
	v_subrev_u32_e32 v14, 46, v0
	s_nop 0
	v_cndmask_b32_e32 v88, v234, v88, vcc
	v_cmp_le_i32_e32 vcc, v14, v237
	v_subrev_u32_e32 v14, 45, v0
	s_nop 0
	v_cndmask_b32_e32 v89, v234, v89, vcc
	v_cmp_le_i32_e32 vcc, v14, v237
	v_subrev_u32_e32 v14, 44, v0
	s_nop 0
	v_cndmask_b32_e32 v90, v234, v90, vcc
	v_cmp_le_i32_e32 vcc, v14, v237
	v_subrev_u32_e32 v14, 39, v0
	s_nop 0
	v_cndmask_b32_e32 v91, v234, v91, vcc
	v_cmp_le_i32_e32 vcc, v14, v237
	v_subrev_u32_e32 v14, 38, v0
	s_nop 0
	v_cndmask_b32_e32 v92, v234, v92, vcc
	v_cmp_le_i32_e32 vcc, v14, v237
	v_subrev_u32_e32 v14, 37, v0
	s_nop 0
	v_cndmask_b32_e32 v93, v234, v93, vcc
	v_cmp_le_i32_e32 vcc, v14, v237
	v_subrev_u32_e32 v14, 36, v0
	s_nop 0
	v_cndmask_b32_e32 v94, v234, v94, vcc
	v_cmp_le_i32_e32 vcc, v14, v237
	v_subrev_u32_e32 v14, 31, v0
	s_nop 0
	v_cndmask_b32_e32 v95, v234, v95, vcc
	v_cmp_le_i32_e32 vcc, v14, v237
	v_subrev_u32_e32 v14, 30, v0
	s_nop 0
	v_cndmask_b32_e32 v64, v234, v64, vcc
	v_cmp_le_i32_e32 vcc, v14, v237
	v_subrev_u32_e32 v14, 29, v0
	s_nop 0
	v_cndmask_b32_e32 v65, v234, v65, vcc
	v_cmp_le_i32_e32 vcc, v14, v237
	v_subrev_u32_e32 v14, 28, v0
	s_nop 0
	v_cndmask_b32_e32 v66, v234, v66, vcc
	v_cmp_le_i32_e32 vcc, v14, v237
	v_subrev_u32_e32 v14, 23, v0
	s_nop 0
	v_cndmask_b32_e32 v67, v234, v67, vcc
	v_cmp_le_i32_e32 vcc, v14, v237
	v_subrev_u32_e32 v14, 22, v0
	s_nop 0
	v_cndmask_b32_e32 v68, v234, v68, vcc
	v_cmp_le_i32_e32 vcc, v14, v237
	v_subrev_u32_e32 v14, 21, v0
	s_nop 0
	v_cndmask_b32_e32 v69, v234, v69, vcc
	v_cmp_le_i32_e32 vcc, v14, v237
	v_subrev_u32_e32 v14, 20, v0
	s_nop 0
	v_cndmask_b32_e32 v70, v234, v70, vcc
	v_cmp_le_i32_e32 vcc, v14, v237
	v_add_u32_e32 v14, -15, v0
	s_nop 0
	v_cndmask_b32_e32 v71, v234, v71, vcc
	v_cmp_le_i32_e32 vcc, v14, v237
	v_add_u32_e32 v14, -14, v0
	s_nop 0
	v_cndmask_b32_e32 v72, v234, v72, vcc
	v_cmp_le_i32_e32 vcc, v14, v237
	v_add_u32_e32 v14, -13, v0
	s_nop 0
	v_cndmask_b32_e32 v73, v234, v73, vcc
	v_cmp_le_i32_e32 vcc, v14, v237
	v_add_u32_e32 v14, -12, v0
	s_nop 0
	v_cndmask_b32_e32 v74, v234, v74, vcc
	v_cmp_le_i32_e32 vcc, v14, v237
	v_add_u32_e32 v14, -7, v0
	s_nop 0
	v_cndmask_b32_e32 v75, v234, v75, vcc
	v_cmp_le_i32_e32 vcc, v14, v237
	v_add_u32_e32 v14, -6, v0
	s_nop 0
	v_cndmask_b32_e32 v76, v234, v76, vcc
	v_cmp_le_i32_e32 vcc, v14, v237
	v_add_u32_e32 v14, -5, v0
	v_add_u32_e32 v0, -4, v0
	v_cndmask_b32_e32 v77, v234, v77, vcc
	v_cmp_le_i32_e32 vcc, v14, v237
	s_nop 1
	v_cndmask_b32_e32 v78, v234, v78, vcc
	v_cmp_le_i32_e32 vcc, v0, v237
	s_nop 1
	v_cndmask_b32_e32 v79, v234, v79, vcc

; template <int DQK, int MODE, bool QN, bool KN> ...
;     ...
;         float ps = 0.f;
; #pragma unroll
;         for (int kb = 0; kb < 2; ++kb)
; #pragma unroll
;           for (int i = 0; i < 16; ++i) { const float pv = __builtin_amdgcn_exp2f(sacc[kb][i] - m_new); sacc[kb][i] = pv; ps += pv; }
;         l_run = l_run * alpha + ps;
.LBB0_1234:
	v_sub_f32_e32 v15, v80, v14
	v_exp_f32_e32 v112, v15
	v_sub_f32_e32 v15, v81, v14
	v_exp_f32_e32 v113, v15
	v_sub_f32_e32 v15, v82, v14
	v_exp_f32_e32 v114, v15
	v_sub_f32_e32 v15, v83, v14
	v_exp_f32_e32 v115, v15
	v_sub_f32_e32 v116, v84, v14
	v_add_f32_e32 v15, 0, v112
	v_exp_f32_e32 v116, v116
	v_sub_f32_e32 v117, v85, v14
	v_add_f32_e32 v15, v113, v15
	v_exp_f32_e32 v117, v117
	v_sub_f32_e32 v118, v86, v14
	v_add_f32_e32 v15, v114, v15
	v_exp_f32_e32 v118, v118
	v_sub_f32_e32 v119, v87, v14
	v_add_f32_e32 v15, v115, v15
	v_exp_f32_e32 v119, v119
	v_sub_f32_e32 v120, v88, v14
	v_add_f32_e32 v15, v116, v15
	v_exp_f32_e32 v120, v120
	v_sub_f32_e32 v121, v89, v14
	v_add_f32_e32 v15, v117, v15
	v_exp_f32_e32 v121, v121
	v_sub_f32_e32 v122, v90, v14
	v_add_f32_e32 v15, v118, v15
	v_exp_f32_e32 v122, v122
	v_sub_f32_e32 v123, v91, v14
	v_add_f32_e32 v15, v119, v15
	v_exp_f32_e32 v123, v123
	v_sub_f32_e32 v124, v92, v14
	v_add_f32_e32 v15, v120, v15
	v_exp_f32_e32 v124, v124
	v_sub_f32_e32 v125, v93, v14
	v_add_f32_e32 v15, v121, v15
	v_exp_f32_e32 v125, v125
	v_sub_f32_e32 v126, v94, v14
	v_add_f32_e32 v15, v122, v15
	v_exp_f32_e32 v126, v126
	v_sub_f32_e32 v127, v95, v14
	v_add_f32_e32 v15, v123, v15
	v_exp_f32_e32 v127, v127
	v_sub_f32_e32 v144, v64, v14
	v_add_f32_e32 v15, v124, v15
	v_exp_f32_e32 v144, v144
	v_sub_f32_e32 v145, v65, v14
	v_add_f32_e32 v15, v125, v15
	v_exp_f32_e32 v145, v145
	v_sub_f32_e32 v146, v66, v14
	v_add_f32_e32 v15, v126, v15
	v_exp_f32_e32 v146, v146
	v_sub_f32_e32 v147, v67, v14
	v_add_f32_e32 v15, v127, v15
	v_exp_f32_e32 v147, v147
	v_sub_f32_e32 v148, v68, v14
	v_add_f32_e32 v15, v144, v15
	v_exp_f32_e32 v148, v148
	v_sub_f32_e32 v149, v69, v14
	v_add_f32_e32 v15, v145, v15
	v_exp_f32_e32 v149, v149
	v_sub_f32_e32 v150, v70, v14
	v_add_f32_e32 v15, v146, v15
	v_exp_f32_e32 v150, v150
	v_sub_f32_e32 v151, v71, v14
	v_add_f32_e32 v15, v147, v15
	v_exp_f32_e32 v151, v151
	v_sub_f32_e32 v152, v72, v14
	v_add_f32_e32 v15, v148, v15
	v_exp_f32_e32 v152, v152
	v_sub_f32_e32 v153, v73, v14
	v_add_f32_e32 v15, v149, v15
	v_exp_f32_e32 v153, v153
	v_sub_f32_e32 v154, v74, v14
	v_add_f32_e32 v15, v150, v15
	v_exp_f32_e32 v154, v154
	v_sub_f32_e32 v155, v75, v14
	v_add_f32_e32 v15, v151, v15
	v_exp_f32_e32 v155, v155
	v_sub_f32_e32 v156, v76, v14
	v_add_f32_e32 v15, v152, v15
	v_exp_f32_e32 v156, v156
	v_sub_f32_e32 v157, v77, v14
	v_add_f32_e32 v15, v153, v15
	v_exp_f32_e32 v157, v157
	v_sub_f32_e32 v158, v78, v14
	v_add_f32_e32 v15, v154, v15
	v_exp_f32_e32 v158, v158
	v_sub_f32_e32 v159, v79, v14
	v_add_f32_e32 v15, v155, v15
	v_exp_f32_e32 v159, v159
	v_add_f32_e32 v15, v156, v15
	v_add_f32_e32 v15, v157, v15
	v_add_f32_e32 v15, v158, v15
	v_add_f32_e32 v15, v159, v15
	v_fmac_f32_e32 v15, v253, v0
	s_cbranch_execnz .LBB0_1196
	s_branch .LBB0_1236

; template <int DQK, int MODE, bool QN, bool KN> ...
;     ...
;       } else if (fixed_shift) {
;         float ps = 0.f;
; #pragma unroll
;         for (int kb = 0; kb < 2; ++kb)
; #pragma unroll
;           for (int i = 0; i < 16; ++i) { const float pv = __builtin_amdgcn_exp2f(sacc[kb][i]); sacc[kb][i] = pv; ps += pv; }
;         l_run += ps;
.LBB0_1236:
	v_exp_f32_e32 v112, v80
	v_exp_f32_e32 v113, v81
	v_exp_f32_e32 v114, v82
	v_exp_f32_e32 v115, v83
	v_add_f32_e32 v0, 0, v112
	v_exp_f32_e32 v116, v84
	v_add_f32_e32 v0, v113, v0
	v_exp_f32_e32 v117, v85
	v_add_f32_e32 v0, v114, v0
	v_exp_f32_e32 v118, v86
	v_add_f32_e32 v0, v115, v0
	v_exp_f32_e32 v119, v87
	v_add_f32_e32 v0, v116, v0
	v_exp_f32_e32 v120, v88
	v_add_f32_e32 v0, v117, v0
	v_exp_f32_e32 v121, v89
	v_add_f32_e32 v0, v118, v0
	v_exp_f32_e32 v122, v90
	v_add_f32_e32 v0, v119, v0
	v_exp_f32_e32 v123, v91
	v_add_f32_e32 v0, v120, v0
	v_exp_f32_e32 v124, v92
	v_add_f32_e32 v0, v121, v0
	v_exp_f32_e32 v125, v93
	v_add_f32_e32 v0, v122, v0
	v_exp_f32_e32 v126, v94
	v_add_f32_e32 v0, v123, v0
	v_exp_f32_e32 v127, v95
	v_add_f32_e32 v0, v124, v0
	v_exp_f32_e32 v144, v64
	v_add_f32_e32 v0, v125, v0
	v_exp_f32_e32 v145, v65
	v_add_f32_e32 v0, v126, v0
	v_exp_f32_e32 v146, v66
	v_add_f32_e32 v0, v127, v0
	v_exp_f32_e32 v147, v67
	v_add_f32_e32 v0, v144, v0
	v_exp_f32_e32 v148, v68
	v_add_f32_e32 v0, v145, v0
	v_exp_f32_e32 v149, v69
	v_add_f32_e32 v0, v146, v0
	v_exp_f32_e32 v150, v70
	v_add_f32_e32 v0, v147, v0
	v_exp_f32_e32 v151, v71
	v_add_f32_e32 v0, v148, v0
	v_exp_f32_e32 v152, v72
	v_add_f32_e32 v0, v149, v0
	v_exp_f32_e32 v153, v73
	v_add_f32_e32 v0, v150, v0
	v_exp_f32_e32 v154, v74
	v_add_f32_e32 v0, v151, v0
	v_exp_f32_e32 v155, v75
	v_add_f32_e32 v0, v152, v0
	v_exp_f32_e32 v156, v76
	v_add_f32_e32 v0, v153, v0
	v_exp_f32_e32 v157, v77
	v_add_f32_e32 v0, v154, v0
	v_exp_f32_e32 v158, v78
	v_add_f32_e32 v0, v155, v0
	v_exp_f32_e32 v159, v79
	v_add_f32_e32 v0, v156, v0
	v_add_f32_e32 v0, v157, v0
	v_add_f32_e32 v0, v158, v0
	v_add_f32_e32 v0, v159, v0
	v_add_f32_e32 v15, v253, v0
	v_mov_b32_e32 v14, v252
	s_branch .LBB0_1196
